# load segments at s_setprio 1 (both setprio inside the load segment, none next to MFMA blocks), MFMA blocks at 0; on top of mergewait
# speedup vs baseline: 1.0102x; 1.0006x over previous
; template <class Epi, class Sched, bool ALIGN_EPI = false, bool SP2 = false>
; __device__ __forceinline__ void gemm_phase(PG8_LAS unsigned char* lds, const Gemm g, const Sched& S, const Epi& E, int tid_in) {
;     ...
;     f32x4 acc[2][2][4][2];
; #pragma unroll
;     for (int a = 0; a < 2; ++a)
; #pragma unroll
;         for (int b = 0; b < 2; ++b)
; #pragma unroll
;             for (int m = 0; m < 4; ++m)
; #pragma unroll
;                 for (int n = 0; n < 2; ++n) acc[a][b][m][n] = (f32x4){0.f, 0.f, 0.f, 0.f};
;     bf16x8 At[4][2], B0[2][2], B1[2][2];
;     const char* cA = (const char*)g.A + (size_t)cur.pm * tstep; const char* cB = (const char*)g.Bt + (size_t)cur.pn * tstep;
;     S.a_ready(cur);
;     if constexpr (SP2) {
;         PG8_STAGE(PG8_SB(0, 0), cB, voffB); PG8_STAGE(PG8_SB(0, 1), cB + hstep, voffB); PG8_STAGE(PG8_SA(0, 0), cA, voffA); PG8_STAGE(PG8_SA(0, 1), cA + hstep, voffA);
;         if (wr == 1) PG8_BAR;
;         PG8_WAIT_V(2); PG8_BAR;
;         PG8_STAGE(PG8_SB(1, 0), cB + kstep, voffB); PG8_STAGE(PG8_SA(1, 0), cA + kstep, voffA); PG8_STAGE(PG8_SB(1, 1), cB + hstep + kstep, voffB);
;         PG8_WAIT_V(6); PG8_BAR;
;     } else {
;         PG8_STAGE(PG8_SB(0, 0), cB, voffB); PG8_STAGE(PG8_SA(0, 0), cA, voffA); PG8_STAGE(PG8_SB(0, 1), cB + hstep, voffB); PG8_STAGE(PG8_SA(0, 1), cA + hstep, voffA);
;         if (wr == 1) PG8_BAR;
;         PG8_WAIT_V(4); PG8_BAR;
;         PG8_STAGE(PG8_SB(1, 0), cB + kstep, voffB); PG8_STAGE(PG8_SA(1, 0), cA + kstep, voffA); PG8_STAGE(PG8_SB(1, 1), cB + hstep + kstep, voffB);
;         PG8_WAIT_V(6); PG8_BAR;
;     }
;     for (;;) {
;         const bool has_next = S.next(ui + 1, nxt);
;         const char* nA = has_next ? (const char*)g.A + (size_t)nxt.pm * tstep : cA; const char* nB = has_next ? (const char*)g.Bt + (size_t)nxt.pn * tstep : cB;
;         for (int t = 0; t < nt; t += 2) {
;             const bool last = (t == nt - 2);
;             const char* a1 = cA + (size_t)(t + 1) * kstep;
;             const char* a2 = last ? nA : cA + (size_t)(t + 2) * kstep; const char* b2 = last ? nB : cB + (size_t)(t + 2) * kstep;
;             const char* a3 = a2 + kstep; const char* b3 = b2 + kstep;
;             if (last && has_next) S.a_ready(nxt);
;             if constexpr (SP2) {
;             PG8_LDB(B0, 0, 0); PG8_LDB(B1, 0, 1); PG8_SCHED; PG8_LDA(At, 0, 0); PG8_STAGE(PG8_SA(1, 1), a1 + hstep, voffA);
.LBB0_109:
	s_ashr_i32 s13, s12, 31
	s_lshl_b64 s[14:15], s[12:13], 20
	s_ashr_i32 s11, s10, 31
	v_lshl_add_u64 v[156:157], v[140:141], 0, s[14:15]
	s_lshl_b64 s[14:15], s[10:11], 20
	v_lshl_add_u64 v[158:159], v[142:143], 0, s[14:15]
	v_mov_b32_e32 v0, 0
	v_cndmask_b32_e64 v131, v5, v157, s[4:5]
	v_cndmask_b32_e64 v160, v4, v156, s[4:5]
	v_cndmask_b32_e64 v161, v3, v159, s[4:5]
	v_cndmask_b32_e64 v162, v2, v158, s[4:5]
	v_lshl_add_u64 v[164:165], v[2:3], 0, s[82:83]
	v_lshl_add_u64 v[166:167], v[4:5], 0, s[86:87]
	s_mov_b32 s11, -2
	v_mov_b32_e32 v1, v0
	v_mov_b32_e32 v2, v0
	v_mov_b32_e32 v3, v0
	v_mov_b32_e32 v4, v0
	v_mov_b32_e32 v5, v0
	v_mov_b32_e32 v6, v0
	v_mov_b32_e32 v7, v0
	v_mov_b32_e32 v8, v0
	v_mov_b32_e32 v9, v0
	v_mov_b32_e32 v10, v0
	v_mov_b32_e32 v11, v0
	v_mov_b32_e32 v16, v0
	v_mov_b32_e32 v17, v0
	v_mov_b32_e32 v18, v0
	v_mov_b32_e32 v19, v0
	v_mov_b32_e32 v24, v0
	v_mov_b32_e32 v25, v0
	v_mov_b32_e32 v26, v0
	v_mov_b32_e32 v27, v0
	v_mov_b32_e32 v32, v0
	v_mov_b32_e32 v33, v0
	v_mov_b32_e32 v34, v0
	v_mov_b32_e32 v35, v0
	v_mov_b32_e32 v40, v0
	v_mov_b32_e32 v41, v0
	v_mov_b32_e32 v42, v0
	v_mov_b32_e32 v43, v0
	v_mov_b32_e32 v48, v0
	v_mov_b32_e32 v49, v0
	v_mov_b32_e32 v50, v0
	v_mov_b32_e32 v51, v0
	v_mov_b32_e32 v12, v0
	v_mov_b32_e32 v13, v0
	v_mov_b32_e32 v14, v0
	v_mov_b32_e32 v15, v0
	v_mov_b32_e32 v20, v0
	v_mov_b32_e32 v21, v0
	v_mov_b32_e32 v22, v0
	v_mov_b32_e32 v23, v0
	v_mov_b32_e32 v28, v0
	v_mov_b32_e32 v29, v0
	v_mov_b32_e32 v30, v0
	v_mov_b32_e32 v31, v0
	v_mov_b32_e32 v36, v0
	v_mov_b32_e32 v37, v0
	v_mov_b32_e32 v38, v0
	v_mov_b32_e32 v39, v0
	v_mov_b32_e32 v44, v0
	v_mov_b32_e32 v45, v0
	v_mov_b32_e32 v46, v0
	v_mov_b32_e32 v47, v0
	v_mov_b32_e32 v52, v0
	v_mov_b32_e32 v53, v0
	v_mov_b32_e32 v54, v0
	v_mov_b32_e32 v55, v0
	v_mov_b32_e32 v56, v0
	v_mov_b32_e32 v57, v0
	v_mov_b32_e32 v58, v0
	v_mov_b32_e32 v59, v0
	v_mov_b32_e32 v60, v0
	v_mov_b32_e32 v61, v0
	v_mov_b32_e32 v62, v0
	v_mov_b32_e32 v63, v0
	v_mov_b32_e32 v64, v0
	v_mov_b32_e32 v65, v0
	v_mov_b32_e32 v66, v0
	v_mov_b32_e32 v67, v0
	v_mov_b32_e32 v68, v0
	v_mov_b32_e32 v69, v0
	v_mov_b32_e32 v70, v0
	v_mov_b32_e32 v71, v0
	v_mov_b32_e32 v72, v0
	v_mov_b32_e32 v73, v0
	v_mov_b32_e32 v74, v0
	v_mov_b32_e32 v75, v0
	v_mov_b32_e32 v80, v0
	v_mov_b32_e32 v81, v0
	v_mov_b32_e32 v82, v0
	v_mov_b32_e32 v83, v0
	v_mov_b32_e32 v88, v0
	v_mov_b32_e32 v89, v0
	v_mov_b32_e32 v90, v0
	v_mov_b32_e32 v91, v0
	v_mov_b32_e32 v96, v0
	v_mov_b32_e32 v97, v0
	v_mov_b32_e32 v98, v0
	v_mov_b32_e32 v99, v0
	v_mov_b32_e32 v104, v0
	v_mov_b32_e32 v105, v0
	v_mov_b32_e32 v106, v0
	v_mov_b32_e32 v107, v0
	v_mov_b32_e32 v112, v0
	v_mov_b32_e32 v113, v0
	v_mov_b32_e32 v114, v0
	v_mov_b32_e32 v115, v0
	v_mov_b32_e32 v76, v0
	v_mov_b32_e32 v77, v0
	v_mov_b32_e32 v78, v0
	v_mov_b32_e32 v79, v0
	v_mov_b32_e32 v84, v0
	v_mov_b32_e32 v85, v0
	v_mov_b32_e32 v86, v0
	v_mov_b32_e32 v87, v0
	v_mov_b32_e32 v92, v0
	v_mov_b32_e32 v93, v0
	v_mov_b32_e32 v94, v0
	v_mov_b32_e32 v95, v0
	v_mov_b32_e32 v100, v0
	v_mov_b32_e32 v101, v0
	v_mov_b32_e32 v102, v0
	v_mov_b32_e32 v103, v0
	v_mov_b32_e32 v108, v0
	v_mov_b32_e32 v109, v0
	v_mov_b32_e32 v110, v0
	v_mov_b32_e32 v111, v0
	v_mov_b32_e32 v116, v0
	v_mov_b32_e32 v117, v0
	v_mov_b32_e32 v118, v0
	v_mov_b32_e32 v119, v0
	v_mov_b32_e32 v120, v0
	v_mov_b32_e32 v121, v0
	v_mov_b32_e32 v122, v0
	v_mov_b32_e32 v123, v0
	v_mov_b32_e32 v124, v0
	v_mov_b32_e32 v125, v0
	v_mov_b32_e32 v126, v0
	v_mov_b32_e32 v127, v0
	s_setprio 1
.LBB0_110:
	s_cmp_eq_u32 s11, 28
	s_cselect_b64 vcc, -1, 0
	s_add_i32 s13, 0, 0x10000
	s_add_i32 s14, 0, 0x14000
	v_lshl_add_u64 v[176:177], v[166:167], 0, s[52:53]
	v_add_u32_e32 v188, s13, v168
	v_add_u32_e32 v204, s14, v168
	v_cndmask_b32_e32 v241, v177, v131, vcc
	v_cndmask_b32_e32 v240, v176, v160, vcc
	ds_read_b128 v[176:179], v188
	ds_read_b128 v[180:183], v188 offset:1024
	ds_read_b128 v[184:187], v188 offset:2048
	ds_read_b128 v[188:191], v188 offset:3072
	ds_read_b128 v[192:195], v204
	ds_read_b128 v[196:199], v204 offset:1024
	ds_read_b128 v[200:203], v204 offset:2048
	ds_read_b128 v[204:207], v204 offset:3072
	v_cndmask_b32_e32 v243, v165, v161, vcc
	v_cndmask_b32_e32 v242, v164, v162, vcc
	v_lshl_add_u64 v[244:245], v[166:167], 0, v[154:155]
	s_add_i32 m0, s18, 0xc000
	ds_read_b128 v[208:211], v175
	ds_read_b128 v[212:215], v175 offset:1024
	ds_read_b128 v[216:219], v175 offset:2048
	ds_read_b128 v[220:223], v175 offset:3072
	ds_read_b128 v[224:227], v175 offset:4096
	ds_read_b128 v[228:231], v175 offset:5120
	ds_read_b128 v[232:235], v175 offset:6144
	ds_read_b128 v[236:239], v175 offset:7168
	global_load_lds_dwordx4 v[244:245], off
	v_lshl_add_u64 v[244:245], v[166:167], 0, v[152:153]
	s_add_i32 m0, s18, 0xe000
	s_nop 0
	global_load_lds_dwordx4 v[244:245], off
	s_setprio 0
	s_waitcnt vmcnt(8) lgkmcnt(0)
	s_barrier
; #define PG8_STAGE(bufoff, gbase, voff) do { _Pragma("unroll") for (int _i = 0; _i < 2; ++_i) \
;         __builtin_amdgcn_global_load_lds((const unsigned*)((const char*)(gbase) + (voff)[_i]), (PG8_LAS unsigned*)(lds + (bufoff) + ldsw + _i * 8192), 16, 0, 0); } while (0)
; #define PG8_LDA(dst, b, h) do { _Pragma("unroll") for (int m = 0; m < 4; ++m) _Pragma("unroll") for (int k = 0; k < 2; ++k) dst[m][k] = *(const PG8_LAS bf16x8*)(lds + PG8_SA(b, h) + aoff + m * 2048 + k * 1024); } while (0)
; #define PG8_MMA(ai, bj, At, Bt) do { __builtin_amdgcn_s_setprio(1); _Pragma("unroll") for (int m = 0; m < 4; ++m) _Pragma("unroll") for (int n = 0; n < 2; ++n) _Pragma("unroll") for (int k = 0; k < 2; ++k) \
;         acc[ai][bj][m][n] = __builtin_amdgcn_mfma_f32_16x16x32_bf16(Bt[n][k], At[m][k], acc[ai][bj][m][n], 0, 0, 0); __builtin_amdgcn_s_setprio(0); } while (0)
; #define PG8_WAIT_V(n) asm volatile("s_waitcnt vmcnt(" #n ")" ::: "memory")
; #define PG8_WAIT_L(n) asm volatile("s_waitcnt lgkmcnt(" #n ")" ::: "memory")
; #define PG8_BAR __builtin_amdgcn_s_barrier()
; #define PG8_SCHED __builtin_amdgcn_sched_barrier(0)
; template <class Epi, class Sched, bool ALIGN_EPI = false, bool SP2 = false>
; __device__ __forceinline__ void gemm_phase(PG8_LAS unsigned char* lds, const Gemm g, const Sched& S, const Epi& E, int tid_in) {
;     ...
;             PG8_WAIT_V(8); PG8_WAIT_L(0); PG8_BAR; PG8_MMA(0, 0, At, B0); PG8_MMA(0, 1, At, B1); PG8_BAR; PG8_SCHED;
;             PG8_LDA(At, 0, 1); PG8_STAGE(PG8_SB(0, 0), b2, voffB); PG8_STAGE(PG8_SB(0, 1), b2 + hstep, voffB); PG8_STAGE(PG8_SA(0, 0), a2, voffA);
;             PG8_WAIT_V(8); PG8_WAIT_L(0); PG8_BAR; PG8_MMA(1, 0, At, B0); PG8_MMA(1, 1, At, B1); PG8_BAR; PG8_SCHED;
	v_mfma_f32_16x16x32_bf16 v[124:127], v[176:179], v[208:211], v[124:127]
	v_mfma_f32_16x16x32_bf16 v[120:123], v[184:187], v[208:211], v[120:123]
	v_mfma_f32_16x16x32_bf16 v[116:119], v[176:179], v[216:219], v[116:119]
	v_mfma_f32_16x16x32_bf16 v[108:111], v[184:187], v[216:219], v[108:111]
	v_mfma_f32_16x16x32_bf16 v[100:103], v[176:179], v[224:227], v[100:103]
	v_mfma_f32_16x16x32_bf16 v[92:95], v[184:187], v[224:227], v[92:95]
	v_mfma_f32_16x16x32_bf16 v[84:87], v[176:179], v[232:235], v[84:87]
	v_mfma_f32_16x16x32_bf16 v[76:79], v[184:187], v[232:235], v[76:79]
	v_mfma_f32_16x16x32_bf16 v[124:127], v[180:183], v[212:215], v[124:127]
	v_mfma_f32_16x16x32_bf16 v[120:123], v[188:191], v[212:215], v[120:123]
	v_mfma_f32_16x16x32_bf16 v[116:119], v[180:183], v[220:223], v[116:119]
	v_mfma_f32_16x16x32_bf16 v[108:111], v[188:191], v[220:223], v[108:111]
	v_mfma_f32_16x16x32_bf16 v[100:103], v[180:183], v[228:231], v[100:103]
	v_mfma_f32_16x16x32_bf16 v[92:95], v[188:191], v[228:231], v[92:95]
	v_mfma_f32_16x16x32_bf16 v[84:87], v[180:183], v[236:239], v[84:87]
	v_mfma_f32_16x16x32_bf16 v[76:79], v[188:191], v[236:239], v[76:79]
	v_mfma_f32_16x16x32_bf16 v[112:115], v[192:195], v[208:211], v[112:115]
	v_mfma_f32_16x16x32_bf16 v[104:107], v[200:203], v[208:211], v[104:107]
	v_mfma_f32_16x16x32_bf16 v[96:99], v[192:195], v[216:219], v[96:99]
	v_mfma_f32_16x16x32_bf16 v[88:91], v[200:203], v[216:219], v[88:91]
	v_mfma_f32_16x16x32_bf16 v[80:83], v[192:195], v[224:227], v[80:83]
	v_mfma_f32_16x16x32_bf16 v[72:75], v[200:203], v[224:227], v[72:75]
	v_mfma_f32_16x16x32_bf16 v[68:71], v[192:195], v[232:235], v[68:71]
	v_mfma_f32_16x16x32_bf16 v[64:67], v[200:203], v[232:235], v[64:67]
	v_mfma_f32_16x16x32_bf16 v[112:115], v[196:199], v[212:215], v[112:115]
	v_mfma_f32_16x16x32_bf16 v[104:107], v[204:207], v[212:215], v[104:107]
	v_mfma_f32_16x16x32_bf16 v[96:99], v[196:199], v[220:223], v[96:99]
	v_mfma_f32_16x16x32_bf16 v[88:91], v[204:207], v[220:223], v[88:91]
	v_mfma_f32_16x16x32_bf16 v[80:83], v[196:199], v[228:231], v[80:83]
	v_mfma_f32_16x16x32_bf16 v[72:75], v[204:207], v[228:231], v[72:75]
	v_mfma_f32_16x16x32_bf16 v[68:71], v[196:199], v[236:239], v[68:71]
	v_mfma_f32_16x16x32_bf16 v[64:67], v[204:207], v[236:239], v[64:67]
	s_barrier
	s_setprio 1
	s_add_i32 s13, s13, s0
	v_lshl_add_u64 v[244:245], v[242:243], 0, v[128:129]
	s_mov_b32 m0, s13
	ds_read_b128 v[208:211], v175 offset:16384
	ds_read_b128 v[212:215], v175 offset:17408
	ds_read_b128 v[216:219], v175 offset:18432
	ds_read_b128 v[220:223], v175 offset:19456
	ds_read_b128 v[224:227], v175 offset:20480
	ds_read_b128 v[228:231], v175 offset:21504
	ds_read_b128 v[232:235], v175 offset:22528
	ds_read_b128 v[236:239], v175 offset:23552
	global_load_lds_dwordx4 v[244:245], off
	v_lshl_add_u64 v[246:247], v[242:243], 0, v[144:145]
	s_add_i32 m0, s13, 0x2000
	v_lshl_add_u64 v[248:249], v[242:243], 0, s[98:99]
	s_add_i32 s13, s14, s0
	global_load_lds_dwordx4 v[246:247], off
	v_lshl_add_u64 v[250:251], v[248:249], 0, v[128:129]
	s_mov_b32 m0, s13
	v_lshl_add_u64 v[248:249], v[248:249], 0, v[144:145]
	global_load_lds_dwordx4 v[250:251], off
	s_add_i32 m0, s13, 0x2000
	v_lshl_add_u64 v[250:251], v[240:241], 0, v[146:147]
	global_load_lds_dwordx4 v[248:249], off
	v_lshl_add_u64 v[248:249], v[240:241], 0, v[148:149]
	s_mov_b32 m0, s18
	s_nop 0
	global_load_lds_dwordx4 v[248:249], off
	s_mov_b32 m0, s19
	s_nop 0
	global_load_lds_dwordx4 v[250:251], off
	s_setprio 0
	s_waitcnt vmcnt(8) lgkmcnt(0)
	s_barrier
	v_mfma_f32_16x16x32_bf16 v[60:63], v[176:179], v[208:211], v[60:63]
	v_mfma_f32_16x16x32_bf16 v[56:59], v[184:187], v[208:211], v[56:59]
	v_mfma_f32_16x16x32_bf16 v[52:55], v[176:179], v[216:219], v[52:55]
	v_mfma_f32_16x16x32_bf16 v[44:47], v[184:187], v[216:219], v[44:47]
	v_mfma_f32_16x16x32_bf16 v[36:39], v[176:179], v[224:227], v[36:39]
	v_mfma_f32_16x16x32_bf16 v[28:31], v[184:187], v[224:227], v[28:31]
	v_mfma_f32_16x16x32_bf16 v[20:23], v[176:179], v[232:235], v[20:23]
	v_mfma_f32_16x16x32_bf16 v[12:15], v[184:187], v[232:235], v[12:15]
	v_mfma_f32_16x16x32_bf16 v[60:63], v[180:183], v[212:215], v[60:63]
	v_mfma_f32_16x16x32_bf16 v[56:59], v[188:191], v[212:215], v[56:59]
	v_mfma_f32_16x16x32_bf16 v[52:55], v[180:183], v[220:223], v[52:55]
	v_mfma_f32_16x16x32_bf16 v[44:47], v[188:191], v[220:223], v[44:47]
	v_mfma_f32_16x16x32_bf16 v[36:39], v[180:183], v[228:231], v[36:39]
	v_mfma_f32_16x16x32_bf16 v[28:31], v[188:191], v[228:231], v[28:31]
	v_mfma_f32_16x16x32_bf16 v[20:23], v[180:183], v[236:239], v[20:23]
	v_mfma_f32_16x16x32_bf16 v[12:15], v[188:191], v[236:239], v[12:15]
	v_mfma_f32_16x16x32_bf16 v[48:51], v[192:195], v[208:211], v[48:51]
	v_mfma_f32_16x16x32_bf16 v[40:43], v[200:203], v[208:211], v[40:43]
	v_mfma_f32_16x16x32_bf16 v[32:35], v[192:195], v[216:219], v[32:35]
	v_mfma_f32_16x16x32_bf16 v[24:27], v[200:203], v[216:219], v[24:27]
	v_mfma_f32_16x16x32_bf16 v[16:19], v[192:195], v[224:227], v[16:19]
	v_mfma_f32_16x16x32_bf16 v[8:11], v[200:203], v[224:227], v[8:11]
	v_mfma_f32_16x16x32_bf16 v[4:7], v[192:195], v[232:235], v[4:7]
	v_mfma_f32_16x16x32_bf16 v[0:3], v[200:203], v[232:235], v[0:3]
	v_mfma_f32_16x16x32_bf16 v[48:51], v[196:199], v[212:215], v[48:51]
	v_mfma_f32_16x16x32_bf16 v[40:43], v[204:207], v[212:215], v[40:43]
	v_mfma_f32_16x16x32_bf16 v[32:35], v[196:199], v[220:223], v[32:35]
	v_mfma_f32_16x16x32_bf16 v[24:27], v[204:207], v[220:223], v[24:27]
	v_mfma_f32_16x16x32_bf16 v[16:19], v[196:199], v[228:231], v[16:19]
	v_mfma_f32_16x16x32_bf16 v[8:11], v[204:207], v[228:231], v[8:11]
	v_mfma_f32_16x16x32_bf16 v[4:7], v[196:199], v[236:239], v[4:7]
	v_mfma_f32_16x16x32_bf16 v[0:3], v[204:207], v[236:239], v[0:3]
	s_barrier
; #define PG8_STAGE(bufoff, gbase, voff) do { _Pragma("unroll") for (int _i = 0; _i < 2; ++_i) \
;         __builtin_amdgcn_global_load_lds((const unsigned*)((const char*)(gbase) + (voff)[_i]), (PG8_LAS unsigned*)(lds + (bufoff) + ldsw + _i * 8192), 16, 0, 0); } while (0)
; #define PG8_LDA(dst, b, h) do { _Pragma("unroll") for (int m = 0; m < 4; ++m) _Pragma("unroll") for (int k = 0; k < 2; ++k) dst[m][k] = *(const PG8_LAS bf16x8*)(lds + PG8_SA(b, h) + aoff + m * 2048 + k * 1024); } while (0)
; #define PG8_LDB(dst, b, h) do { _Pragma("unroll") for (int n = 0; n < 2; ++n) _Pragma("unroll") for (int k = 0; k < 2; ++k) dst[n][k] = *(const PG8_LAS bf16x8*)(lds + PG8_SB(b, h) + boff + n * 2048 + k * 1024); } while (0)
; #define PG8_MMA(ai, bj, At, Bt) do { __builtin_amdgcn_s_setprio(1); _Pragma("unroll") for (int m = 0; m < 4; ++m) _Pragma("unroll") for (int n = 0; n < 2; ++n) _Pragma("unroll") for (int k = 0; k < 2; ++k) \
;         acc[ai][bj][m][n] = __builtin_amdgcn_mfma_f32_16x16x32_bf16(Bt[n][k], At[m][k], acc[ai][bj][m][n], 0, 0, 0); __builtin_amdgcn_s_setprio(0); } while (0)
; #define PG8_WAIT_V(n) asm volatile("s_waitcnt vmcnt(" #n ")" ::: "memory")
; #define PG8_WAIT_L(n) asm volatile("s_waitcnt lgkmcnt(" #n ")" ::: "memory")
; #define PG8_BAR __builtin_amdgcn_s_barrier()
; #define PG8_SCHED __builtin_amdgcn_sched_barrier(0)
; template <class Epi, class Sched, bool ALIGN_EPI = false, bool SP2 = false>
; __device__ __forceinline__ void gemm_phase(PG8_LAS unsigned char* lds, const Gemm g, const Sched& S, const Epi& E, int tid_in) {
;     ...
;             PG8_LDB(B0, 1, 0); PG8_LDB(B1, 1, 1); PG8_SCHED; PG8_LDA(At, 1, 0); PG8_STAGE(PG8_SA(0, 1), a2 + hstep, voffA);
;             PG8_WAIT_V(8); PG8_WAIT_L(0); PG8_BAR; PG8_MMA(0, 0, At, B0); PG8_MMA(0, 1, At, B1); PG8_BAR; PG8_SCHED;
	s_setprio 1
	s_add_i32 s13, 0, 0x18000
	s_add_i32 s14, 0, 0x1c000
	v_add_u32_e32 v188, s13, v168
	v_add_u32_e32 v204, s14, v168
	ds_read_b128 v[176:179], v188
	ds_read_b128 v[180:183], v188 offset:1024
	ds_read_b128 v[184:187], v188 offset:2048
	ds_read_b128 v[188:191], v188 offset:3072
	ds_read_b128 v[192:195], v204
	ds_read_b128 v[196:199], v204 offset:1024
	ds_read_b128 v[200:203], v204 offset:2048
	ds_read_b128 v[204:207], v204 offset:3072
	v_lshl_add_u64 v[240:241], v[240:241], 0, s[98:99]
	s_mov_b32 m0, s20
	v_lshl_add_u64 v[252:253], v[240:241], 0, v[148:149]
	ds_read_b128 v[208:211], v175 offset:32768
	ds_read_b128 v[212:215], v175 offset:33792
	ds_read_b128 v[216:219], v175 offset:34816
	ds_read_b128 v[220:223], v175 offset:35840
	ds_read_b128 v[224:227], v175 offset:36864
	ds_read_b128 v[228:231], v175 offset:37888
	ds_read_b128 v[232:235], v175 offset:38912
	ds_read_b128 v[236:239], v175 offset:39936
	global_load_lds_dwordx4 v[252:253], off
	v_lshl_add_u64 v[240:241], v[240:241], 0, v[146:147]
	s_mov_b32 m0, s21
	s_nop 0
	global_load_lds_dwordx4 v[240:241], off
	s_setprio 0
	s_waitcnt vmcnt(8) lgkmcnt(0)
	s_barrier
	v_mfma_f32_16x16x32_bf16 v[124:127], v[176:179], v[208:211], v[124:127]
	v_mfma_f32_16x16x32_bf16 v[120:123], v[184:187], v[208:211], v[120:123]
	v_mfma_f32_16x16x32_bf16 v[116:119], v[176:179], v[216:219], v[116:119]
	v_mfma_f32_16x16x32_bf16 v[108:111], v[184:187], v[216:219], v[108:111]
	v_mfma_f32_16x16x32_bf16 v[100:103], v[176:179], v[224:227], v[100:103]
	v_mfma_f32_16x16x32_bf16 v[92:95], v[184:187], v[224:227], v[92:95]
	v_mfma_f32_16x16x32_bf16 v[84:87], v[176:179], v[232:235], v[84:87]
	v_mfma_f32_16x16x32_bf16 v[76:79], v[184:187], v[232:235], v[76:79]
	v_mfma_f32_16x16x32_bf16 v[124:127], v[180:183], v[212:215], v[124:127]
	v_mfma_f32_16x16x32_bf16 v[120:123], v[188:191], v[212:215], v[120:123]
	v_mfma_f32_16x16x32_bf16 v[116:119], v[180:183], v[220:223], v[116:119]
	v_mfma_f32_16x16x32_bf16 v[108:111], v[188:191], v[220:223], v[108:111]
	v_mfma_f32_16x16x32_bf16 v[100:103], v[180:183], v[228:231], v[100:103]
	v_mfma_f32_16x16x32_bf16 v[92:95], v[188:191], v[228:231], v[92:95]
	v_mfma_f32_16x16x32_bf16 v[84:87], v[180:183], v[236:239], v[84:87]
	v_mfma_f32_16x16x32_bf16 v[76:79], v[188:191], v[236:239], v[76:79]
	v_mfma_f32_16x16x32_bf16 v[112:115], v[192:195], v[208:211], v[112:115]
	v_mfma_f32_16x16x32_bf16 v[104:107], v[200:203], v[208:211], v[104:107]
	v_mfma_f32_16x16x32_bf16 v[96:99], v[192:195], v[216:219], v[96:99]
	v_mfma_f32_16x16x32_bf16 v[88:91], v[200:203], v[216:219], v[88:91]
	v_mfma_f32_16x16x32_bf16 v[80:83], v[192:195], v[224:227], v[80:83]
	v_mfma_f32_16x16x32_bf16 v[72:75], v[200:203], v[224:227], v[72:75]
	v_mfma_f32_16x16x32_bf16 v[68:71], v[192:195], v[232:235], v[68:71]
	v_mfma_f32_16x16x32_bf16 v[64:67], v[200:203], v[232:235], v[64:67]
	v_mfma_f32_16x16x32_bf16 v[112:115], v[196:199], v[212:215], v[112:115]
	v_mfma_f32_16x16x32_bf16 v[104:107], v[204:207], v[212:215], v[104:107]
	v_mfma_f32_16x16x32_bf16 v[96:99], v[196:199], v[220:223], v[96:99]
	v_mfma_f32_16x16x32_bf16 v[88:91], v[204:207], v[220:223], v[88:91]
	v_mfma_f32_16x16x32_bf16 v[80:83], v[196:199], v[228:231], v[80:83]
	v_mfma_f32_16x16x32_bf16 v[72:75], v[204:207], v[228:231], v[72:75]
	v_mfma_f32_16x16x32_bf16 v[68:71], v[196:199], v[236:239], v[68:71]
	v_mfma_f32_16x16x32_bf16 v[64:67], v[204:207], v[236:239], v[64:67]
	s_barrier
; #define PG8_STAGE(bufoff, gbase, voff) do { _Pragma("unroll") for (int _i = 0; _i < 2; ++_i) \
;         __builtin_amdgcn_global_load_lds((const unsigned*)((const char*)(gbase) + (voff)[_i]), (PG8_LAS unsigned*)(lds + (bufoff) + ldsw + _i * 8192), 16, 0, 0); } while (0)
; #define PG8_LDA(dst, b, h) do { _Pragma("unroll") for (int m = 0; m < 4; ++m) _Pragma("unroll") for (int k = 0; k < 2; ++k) dst[m][k] = *(const PG8_LAS bf16x8*)(lds + PG8_SA(b, h) + aoff + m * 2048 + k * 1024); } while (0)
; #define PG8_MMA(ai, bj, At, Bt) do { __builtin_amdgcn_s_setprio(1); _Pragma("unroll") for (int m = 0; m < 4; ++m) _Pragma("unroll") for (int n = 0; n < 2; ++n) _Pragma("unroll") for (int k = 0; k < 2; ++k) \
;         acc[ai][bj][m][n] = __builtin_amdgcn_mfma_f32_16x16x32_bf16(Bt[n][k], At[m][k], acc[ai][bj][m][n], 0, 0, 0); __builtin_amdgcn_s_setprio(0); } while (0)
; #define PG8_WAIT_V(n) asm volatile("s_waitcnt vmcnt(" #n ")" ::: "memory")
; #define PG8_WAIT_L(n) asm volatile("s_waitcnt lgkmcnt(" #n ")" ::: "memory")
; #define PG8_BAR __builtin_amdgcn_s_barrier()
; #define PG8_SCHED __builtin_amdgcn_sched_barrier(0)
; template <class Epi, class Sched, bool ALIGN_EPI = false, bool SP2 = false>
; __device__ __forceinline__ void gemm_phase(PG8_LAS unsigned char* lds, const Gemm g, const Sched& S, const Epi& E, int tid_in) {
;     ...
;         for (int t = 0; t < nt; t += 2) {
;             const bool last = (t == nt - 2);
;     ...
;             PG8_LDA(At, 1, 1); PG8_STAGE(PG8_SB(1, 0), b3, voffB); PG8_STAGE(PG8_SB(1, 1), b3 + hstep, voffB); PG8_STAGE(PG8_SA(1, 0), a3, voffA);
;             PG8_WAIT_V(8); PG8_WAIT_L(0); PG8_BAR; PG8_MMA(1, 0, At, B0); PG8_MMA(1, 1, At, B1); PG8_BAR; PG8_SCHED;
	s_setprio 1
	s_add_i32 s13, s13, s0
	v_lshl_add_u64 v[240:241], v[244:245], 0, s[70:71]
	s_mov_b32 m0, s13
	ds_read_b128 v[208:211], v175 offset:49152
	ds_read_b128 v[212:215], v175 offset:50176
	ds_read_b128 v[216:219], v175 offset:51200
	ds_read_b128 v[220:223], v175 offset:52224
	ds_read_b128 v[224:227], v175 offset:53248
	ds_read_b128 v[228:231], v175 offset:54272
	ds_read_b128 v[232:235], v175 offset:55296
	ds_read_b128 v[236:239], v175 offset:56320
	global_load_lds_dwordx4 v[240:241], off
	v_lshl_add_u64 v[240:241], v[246:247], 0, s[70:71]
	s_add_i32 m0, s13, 0x2000
	s_add_i32 s13, s14, s0
	global_load_lds_dwordx4 v[240:241], off
	v_lshl_add_u64 v[240:241], v[242:243], 0, s[86:87]
	v_lshl_add_u64 v[242:243], v[240:241], 0, v[128:129]
	s_mov_b32 m0, s13
	v_lshl_add_u64 v[240:241], v[240:241], 0, v[144:145]
	global_load_lds_dwordx4 v[242:243], off
	s_add_i32 m0, s13, 0x2000
	s_nop 0
	global_load_lds_dwordx4 v[240:241], off
	v_lshl_add_u64 v[240:241], v[248:249], 0, s[70:71]
	s_mov_b32 m0, s22
	s_nop 0
	global_load_lds_dwordx4 v[240:241], off
	v_lshl_add_u64 v[240:241], v[250:251], 0, s[70:71]
	s_mov_b32 m0, s23
	s_nop 0
	global_load_lds_dwordx4 v[240:241], off
	s_setprio 0
	s_waitcnt vmcnt(8) lgkmcnt(0)
	s_barrier
	v_mfma_f32_16x16x32_bf16 v[60:63], v[176:179], v[208:211], v[60:63]
	v_mfma_f32_16x16x32_bf16 v[56:59], v[184:187], v[208:211], v[56:59]
	v_mfma_f32_16x16x32_bf16 v[52:55], v[176:179], v[216:219], v[52:55]
	v_mfma_f32_16x16x32_bf16 v[44:47], v[184:187], v[216:219], v[44:47]
	v_mfma_f32_16x16x32_bf16 v[36:39], v[176:179], v[224:227], v[36:39]
	v_mfma_f32_16x16x32_bf16 v[28:31], v[184:187], v[224:227], v[28:31]
	v_mfma_f32_16x16x32_bf16 v[20:23], v[176:179], v[232:235], v[20:23]
	v_mfma_f32_16x16x32_bf16 v[12:15], v[184:187], v[232:235], v[12:15]
	v_mfma_f32_16x16x32_bf16 v[60:63], v[180:183], v[212:215], v[60:63]
	v_mfma_f32_16x16x32_bf16 v[56:59], v[188:191], v[212:215], v[56:59]
	v_mfma_f32_16x16x32_bf16 v[52:55], v[180:183], v[220:223], v[52:55]
	v_mfma_f32_16x16x32_bf16 v[44:47], v[188:191], v[220:223], v[44:47]
	v_mfma_f32_16x16x32_bf16 v[36:39], v[180:183], v[228:231], v[36:39]
	v_mfma_f32_16x16x32_bf16 v[28:31], v[188:191], v[228:231], v[28:31]
	v_mfma_f32_16x16x32_bf16 v[20:23], v[180:183], v[236:239], v[20:23]
	v_mfma_f32_16x16x32_bf16 v[12:15], v[188:191], v[236:239], v[12:15]
	v_mfma_f32_16x16x32_bf16 v[48:51], v[192:195], v[208:211], v[48:51]
	v_mfma_f32_16x16x32_bf16 v[40:43], v[200:203], v[208:211], v[40:43]
	v_mfma_f32_16x16x32_bf16 v[32:35], v[192:195], v[216:219], v[32:35]
	v_mfma_f32_16x16x32_bf16 v[24:27], v[200:203], v[216:219], v[24:27]
	v_mfma_f32_16x16x32_bf16 v[16:19], v[192:195], v[224:227], v[16:19]
	v_mfma_f32_16x16x32_bf16 v[8:11], v[200:203], v[224:227], v[8:11]
	v_mfma_f32_16x16x32_bf16 v[4:7], v[192:195], v[232:235], v[4:7]
	v_mfma_f32_16x16x32_bf16 v[0:3], v[200:203], v[232:235], v[0:3]
	v_mfma_f32_16x16x32_bf16 v[48:51], v[196:199], v[212:215], v[48:51]
	v_mfma_f32_16x16x32_bf16 v[40:43], v[204:207], v[212:215], v[40:43]
	v_mfma_f32_16x16x32_bf16 v[32:35], v[196:199], v[220:223], v[32:35]
	v_mfma_f32_16x16x32_bf16 v[24:27], v[204:207], v[220:223], v[24:27]
	v_mfma_f32_16x16x32_bf16 v[16:19], v[196:199], v[228:231], v[16:19]
	v_mfma_f32_16x16x32_bf16 v[8:11], v[204:207], v[228:231], v[8:11]
	v_mfma_f32_16x16x32_bf16 v[4:7], v[196:199], v[236:239], v[4:7]
	v_mfma_f32_16x16x32_bf16 v[0:3], v[204:207], v[236:239], v[0:3]
	s_barrier
	s_setprio 1
	s_add_i32 s11, s11, 2
	v_lshl_add_u64 v[164:165], v[164:165], 0, s[82:83]
	s_cmp_gt_u32 s11, 29
	v_lshl_add_u64 v[166:167], v[166:167], 0, s[82:83]
	s_cbranch_scc0 .LBB0_110
	s_setprio 0
	s_and_b64 vcc, exec, s[8:9]
	s_cbranch_vccz .LBB0_113
	s_barrier

; template <class Epi, class Sched, bool ALIGN_EPI = false, bool SP2 = false>
; __device__ __forceinline__ void gemm_phase(PG8_LAS unsigned char* lds, const Gemm g, const Sched& S, const Epi& E, int tid_in) {
;     ...
;         const char* nA = has_next ? (const char*)g.A + (size_t)nxt.pm * tstep : cA; const char* nB = has_next ? (const char*)g.Bt + (size_t)nxt.pn * tstep : cB;
;         for (int t = 0; t < nt; t += 2) {
;             const bool last = (t == nt - 2);
;             const char* a1 = cA + (size_t)(t + 1) * kstep;
;             const char* a2 = last ? nA : cA + (size_t)(t + 2) * kstep; const char* b2 = last ? nB : cB + (size_t)(t + 2) * kstep;
;             const char* a3 = a2 + kstep; const char* b3 = b2 + kstep;
;             if (last && has_next) S.a_ready(nxt);
;     ...
;         for (int a = 0; a < 2; ++a)
; #pragma unroll
;             for (int b = 0; b < 2; ++b)
; #pragma unroll
;                 for (int m = 0; m < 4; ++m)
; #pragma unroll
;                     for (int n = 0; n < 2; ++n) acc[a][b][m][n] = (f32x4){0.f, 0.f, 0.f, 0.f};
;         cur = nxt; cA = nA; cB = nB; ++ui;
.LBB0_404:
	s_ashr_i32 s15, s14, 31
	s_lshl_b64 s[2:3], s[14:15], 20
	s_ashr_i32 s13, s12, 31
	v_lshl_add_u64 v[156:157], v[140:141], 0, s[2:3]
	s_lshl_b64 s[2:3], s[12:13], 20
	v_lshl_add_u64 v[158:159], v[142:143], 0, s[2:3]
	v_cndmask_b32_e64 v162, v0, v158, s[6:7]
	v_lshl_add_u64 v[164:165], v[0:1], 0, s[82:83]
	v_mov_b32_e32 v0, 0
	v_cndmask_b32_e64 v131, v3, v157, s[6:7]
	v_cndmask_b32_e64 v160, v2, v156, s[6:7]
	v_cndmask_b32_e64 v161, v1, v159, s[6:7]
	v_lshl_add_u64 v[166:167], v[2:3], 0, s[86:87]
	s_mov_b32 s2, -2
	v_mov_b32_e32 v1, v0
	v_mov_b32_e32 v2, v0
	v_mov_b32_e32 v3, v0
	v_mov_b32_e32 v4, v0
	v_mov_b32_e32 v5, v0
	v_mov_b32_e32 v6, v0
	v_mov_b32_e32 v7, v0
	v_mov_b32_e32 v8, v0
	v_mov_b32_e32 v9, v0
	v_mov_b32_e32 v10, v0
	v_mov_b32_e32 v11, v0
	v_mov_b32_e32 v16, v0
	v_mov_b32_e32 v17, v0
	v_mov_b32_e32 v18, v0
	v_mov_b32_e32 v19, v0
	v_mov_b32_e32 v24, v0
	v_mov_b32_e32 v25, v0
	v_mov_b32_e32 v26, v0
	v_mov_b32_e32 v27, v0
	v_mov_b32_e32 v32, v0
	v_mov_b32_e32 v33, v0
	v_mov_b32_e32 v34, v0
	v_mov_b32_e32 v35, v0
	v_mov_b32_e32 v40, v0
	v_mov_b32_e32 v41, v0
	v_mov_b32_e32 v42, v0
	v_mov_b32_e32 v43, v0
	v_mov_b32_e32 v48, v0
	v_mov_b32_e32 v49, v0
	v_mov_b32_e32 v50, v0
	v_mov_b32_e32 v51, v0
	v_mov_b32_e32 v12, v0
	v_mov_b32_e32 v13, v0
	v_mov_b32_e32 v14, v0
	v_mov_b32_e32 v15, v0
	v_mov_b32_e32 v20, v0
	v_mov_b32_e32 v21, v0
	v_mov_b32_e32 v22, v0
	v_mov_b32_e32 v23, v0
	v_mov_b32_e32 v28, v0
	v_mov_b32_e32 v29, v0
	v_mov_b32_e32 v30, v0
	v_mov_b32_e32 v31, v0
	v_mov_b32_e32 v36, v0
	v_mov_b32_e32 v37, v0
	v_mov_b32_e32 v38, v0
	v_mov_b32_e32 v39, v0
	v_mov_b32_e32 v44, v0
	v_mov_b32_e32 v45, v0
	v_mov_b32_e32 v46, v0
	v_mov_b32_e32 v47, v0
	v_mov_b32_e32 v52, v0
	v_mov_b32_e32 v53, v0
	v_mov_b32_e32 v54, v0
	v_mov_b32_e32 v55, v0
	v_mov_b32_e32 v56, v0
	v_mov_b32_e32 v57, v0
	v_mov_b32_e32 v58, v0
	v_mov_b32_e32 v59, v0
	v_mov_b32_e32 v60, v0
	v_mov_b32_e32 v61, v0
	v_mov_b32_e32 v62, v0
	v_mov_b32_e32 v63, v0
	v_mov_b32_e32 v64, v0
	v_mov_b32_e32 v65, v0
	v_mov_b32_e32 v66, v0
	v_mov_b32_e32 v67, v0
	v_mov_b32_e32 v68, v0
	v_mov_b32_e32 v69, v0
	v_mov_b32_e32 v70, v0
	v_mov_b32_e32 v71, v0
	v_mov_b32_e32 v72, v0
	v_mov_b32_e32 v73, v0
	v_mov_b32_e32 v74, v0
	v_mov_b32_e32 v75, v0
	v_mov_b32_e32 v80, v0
	v_mov_b32_e32 v81, v0
	v_mov_b32_e32 v82, v0
	v_mov_b32_e32 v83, v0
	v_mov_b32_e32 v88, v0
	v_mov_b32_e32 v89, v0
	v_mov_b32_e32 v90, v0
	v_mov_b32_e32 v91, v0
	v_mov_b32_e32 v96, v0
	v_mov_b32_e32 v97, v0
	v_mov_b32_e32 v98, v0
	v_mov_b32_e32 v99, v0
	v_mov_b32_e32 v104, v0
	v_mov_b32_e32 v105, v0
	v_mov_b32_e32 v106, v0
	v_mov_b32_e32 v107, v0
	v_mov_b32_e32 v112, v0
	v_mov_b32_e32 v113, v0
	v_mov_b32_e32 v114, v0
	v_mov_b32_e32 v115, v0
	v_mov_b32_e32 v76, v0
	v_mov_b32_e32 v77, v0
	v_mov_b32_e32 v78, v0
	v_mov_b32_e32 v79, v0
	v_mov_b32_e32 v84, v0
	v_mov_b32_e32 v85, v0
	v_mov_b32_e32 v86, v0
	v_mov_b32_e32 v87, v0
	v_mov_b32_e32 v92, v0
	v_mov_b32_e32 v93, v0
	v_mov_b32_e32 v94, v0
	v_mov_b32_e32 v95, v0
	v_mov_b32_e32 v100, v0
	v_mov_b32_e32 v101, v0
	v_mov_b32_e32 v102, v0
	v_mov_b32_e32 v103, v0
	v_mov_b32_e32 v108, v0
	v_mov_b32_e32 v109, v0
	v_mov_b32_e32 v110, v0
	v_mov_b32_e32 v111, v0
	v_mov_b32_e32 v116, v0
	v_mov_b32_e32 v117, v0
	v_mov_b32_e32 v118, v0
	v_mov_b32_e32 v119, v0
	v_mov_b32_e32 v120, v0
	v_mov_b32_e32 v121, v0
	v_mov_b32_e32 v122, v0
	v_mov_b32_e32 v123, v0
	v_mov_b32_e32 v124, v0
	v_mov_b32_e32 v125, v0
	v_mov_b32_e32 v126, v0
	v_mov_b32_e32 v127, v0
	s_setprio 1
.LBB0_405:
	s_cmp_eq_u32 s2, 28
	s_cselect_b64 vcc, -1, 0
	s_add_i32 s3, 0, 0x10000
	s_add_i32 s13, 0, 0x14000
	v_lshl_add_u64 v[176:177], v[166:167], 0, s[52:53]
	v_add_u32_e32 v188, s3, v168
	v_add_u32_e32 v204, s13, v168
	v_cndmask_b32_e32 v241, v177, v131, vcc
	v_cndmask_b32_e32 v240, v176, v160, vcc
	ds_read_b128 v[176:179], v188
	ds_read_b128 v[180:183], v188 offset:1024
	ds_read_b128 v[184:187], v188 offset:2048
	ds_read_b128 v[188:191], v188 offset:3072
	ds_read_b128 v[192:195], v204
	ds_read_b128 v[196:199], v204 offset:1024
	ds_read_b128 v[200:203], v204 offset:2048
	ds_read_b128 v[204:207], v204 offset:3072
	v_cndmask_b32_e32 v243, v165, v161, vcc
	v_cndmask_b32_e32 v242, v164, v162, vcc
	v_lshl_add_u64 v[244:245], v[166:167], 0, v[154:155]
	s_add_i32 m0, s16, 0xc000
	ds_read_b128 v[208:211], v175
	ds_read_b128 v[212:215], v175 offset:1024
	ds_read_b128 v[216:219], v175 offset:2048
	ds_read_b128 v[220:223], v175 offset:3072
	ds_read_b128 v[224:227], v175 offset:4096
	ds_read_b128 v[228:231], v175 offset:5120
	ds_read_b128 v[232:235], v175 offset:6144
	ds_read_b128 v[236:239], v175 offset:7168
	global_load_lds_dwordx4 v[244:245], off
	v_lshl_add_u64 v[244:245], v[166:167], 0, v[152:153]
	s_add_i32 m0, s16, 0xe000
	s_nop 0
	global_load_lds_dwordx4 v[244:245], off
	s_setprio 0
	s_waitcnt vmcnt(8) lgkmcnt(0)
	s_barrier
; #define PG8_STAGE(bufoff, gbase, voff) do { _Pragma("unroll") for (int _i = 0; _i < 2; ++_i) \
;         __builtin_amdgcn_global_load_lds((const unsigned*)((const char*)(gbase) + (voff)[_i]), (PG8_LAS unsigned*)(lds + (bufoff) + ldsw + _i * 8192), 16, 0, 0); } while (0)
; #define PG8_LDA(dst, b, h) do { _Pragma("unroll") for (int m = 0; m < 4; ++m) _Pragma("unroll") for (int k = 0; k < 2; ++k) dst[m][k] = *(const PG8_LAS bf16x8*)(lds + PG8_SA(b, h) + aoff + m * 2048 + k * 1024); } while (0)
; #define PG8_MMA(ai, bj, At, Bt) do { __builtin_amdgcn_s_setprio(1); _Pragma("unroll") for (int m = 0; m < 4; ++m) _Pragma("unroll") for (int n = 0; n < 2; ++n) _Pragma("unroll") for (int k = 0; k < 2; ++k) \
;         acc[ai][bj][m][n] = __builtin_amdgcn_mfma_f32_16x16x32_bf16(Bt[n][k], At[m][k], acc[ai][bj][m][n], 0, 0, 0); __builtin_amdgcn_s_setprio(0); } while (0)
; #define PG8_WAIT_V(n) asm volatile("s_waitcnt vmcnt(" #n ")" ::: "memory")
; #define PG8_WAIT_L(n) asm volatile("s_waitcnt lgkmcnt(" #n ")" ::: "memory")
; #define PG8_BAR __builtin_amdgcn_s_barrier()
; #define PG8_SCHED __builtin_amdgcn_sched_barrier(0)
; template <class Epi, class Sched, bool ALIGN_EPI = false, bool SP2 = false>
; __device__ __forceinline__ void gemm_phase(PG8_LAS unsigned char* lds, const Gemm g, const Sched& S, const Epi& E, int tid_in) {
;     ...
;             PG8_WAIT_V(8); PG8_WAIT_L(0); PG8_BAR; PG8_MMA(0, 0, At, B0); PG8_MMA(0, 1, At, B1); PG8_BAR; PG8_SCHED;
;             PG8_LDA(At, 0, 1); PG8_STAGE(PG8_SB(0, 0), b2, voffB); PG8_STAGE(PG8_SB(0, 1), b2 + hstep, voffB); PG8_STAGE(PG8_SA(0, 0), a2, voffA);
;             PG8_WAIT_V(8); PG8_WAIT_L(0); PG8_BAR; PG8_MMA(1, 0, At, B0); PG8_MMA(1, 1, At, B1); PG8_BAR; PG8_SCHED;
	v_mfma_f32_16x16x32_bf16 v[124:127], v[176:179], v[208:211], v[124:127]
	v_mfma_f32_16x16x32_bf16 v[120:123], v[184:187], v[208:211], v[120:123]
	v_mfma_f32_16x16x32_bf16 v[116:119], v[176:179], v[216:219], v[116:119]
	v_mfma_f32_16x16x32_bf16 v[108:111], v[184:187], v[216:219], v[108:111]
	v_mfma_f32_16x16x32_bf16 v[100:103], v[176:179], v[224:227], v[100:103]
	v_mfma_f32_16x16x32_bf16 v[92:95], v[184:187], v[224:227], v[92:95]
	v_mfma_f32_16x16x32_bf16 v[84:87], v[176:179], v[232:235], v[84:87]
	v_mfma_f32_16x16x32_bf16 v[76:79], v[184:187], v[232:235], v[76:79]
	v_mfma_f32_16x16x32_bf16 v[124:127], v[180:183], v[212:215], v[124:127]
	v_mfma_f32_16x16x32_bf16 v[120:123], v[188:191], v[212:215], v[120:123]
	v_mfma_f32_16x16x32_bf16 v[116:119], v[180:183], v[220:223], v[116:119]
	v_mfma_f32_16x16x32_bf16 v[108:111], v[188:191], v[220:223], v[108:111]
	v_mfma_f32_16x16x32_bf16 v[100:103], v[180:183], v[228:231], v[100:103]
	v_mfma_f32_16x16x32_bf16 v[92:95], v[188:191], v[228:231], v[92:95]
	v_mfma_f32_16x16x32_bf16 v[84:87], v[180:183], v[236:239], v[84:87]
	v_mfma_f32_16x16x32_bf16 v[76:79], v[188:191], v[236:239], v[76:79]
	v_mfma_f32_16x16x32_bf16 v[112:115], v[192:195], v[208:211], v[112:115]
	v_mfma_f32_16x16x32_bf16 v[104:107], v[200:203], v[208:211], v[104:107]
	v_mfma_f32_16x16x32_bf16 v[96:99], v[192:195], v[216:219], v[96:99]
	v_mfma_f32_16x16x32_bf16 v[88:91], v[200:203], v[216:219], v[88:91]
	v_mfma_f32_16x16x32_bf16 v[80:83], v[192:195], v[224:227], v[80:83]
	v_mfma_f32_16x16x32_bf16 v[72:75], v[200:203], v[224:227], v[72:75]
	v_mfma_f32_16x16x32_bf16 v[68:71], v[192:195], v[232:235], v[68:71]
	v_mfma_f32_16x16x32_bf16 v[64:67], v[200:203], v[232:235], v[64:67]
	v_mfma_f32_16x16x32_bf16 v[112:115], v[196:199], v[212:215], v[112:115]
	v_mfma_f32_16x16x32_bf16 v[104:107], v[204:207], v[212:215], v[104:107]
	v_mfma_f32_16x16x32_bf16 v[96:99], v[196:199], v[220:223], v[96:99]
	v_mfma_f32_16x16x32_bf16 v[88:91], v[204:207], v[220:223], v[88:91]
	v_mfma_f32_16x16x32_bf16 v[80:83], v[196:199], v[228:231], v[80:83]
	v_mfma_f32_16x16x32_bf16 v[72:75], v[204:207], v[228:231], v[72:75]
	v_mfma_f32_16x16x32_bf16 v[68:71], v[196:199], v[236:239], v[68:71]
	v_mfma_f32_16x16x32_bf16 v[64:67], v[204:207], v[236:239], v[64:67]
	s_barrier
	s_setprio 1
	s_add_i32 s3, s3, s1
	v_lshl_add_u64 v[244:245], v[242:243], 0, v[128:129]
	s_mov_b32 m0, s3
	ds_read_b128 v[208:211], v175 offset:16384
	ds_read_b128 v[212:215], v175 offset:17408
	ds_read_b128 v[216:219], v175 offset:18432
	ds_read_b128 v[220:223], v175 offset:19456
	ds_read_b128 v[224:227], v175 offset:20480
	ds_read_b128 v[228:231], v175 offset:21504
	ds_read_b128 v[232:235], v175 offset:22528
	ds_read_b128 v[236:239], v175 offset:23552
	global_load_lds_dwordx4 v[244:245], off
	v_lshl_add_u64 v[246:247], v[242:243], 0, v[144:145]
	s_add_i32 m0, s3, 0x2000
	v_lshl_add_u64 v[248:249], v[242:243], 0, s[98:99]
	s_add_i32 s3, s13, s1
	global_load_lds_dwordx4 v[246:247], off
	v_lshl_add_u64 v[250:251], v[248:249], 0, v[128:129]
	s_mov_b32 m0, s3
	v_lshl_add_u64 v[248:249], v[248:249], 0, v[144:145]
	global_load_lds_dwordx4 v[250:251], off
	s_add_i32 m0, s3, 0x2000
	v_lshl_add_u64 v[250:251], v[240:241], 0, v[146:147]
	global_load_lds_dwordx4 v[248:249], off
	v_lshl_add_u64 v[248:249], v[240:241], 0, v[148:149]
	s_mov_b32 m0, s16
	s_nop 0
	global_load_lds_dwordx4 v[248:249], off
	s_mov_b32 m0, s17
	s_nop 0
	global_load_lds_dwordx4 v[250:251], off
	s_setprio 0
	s_waitcnt vmcnt(8) lgkmcnt(0)
	s_barrier
	v_mfma_f32_16x16x32_bf16 v[60:63], v[176:179], v[208:211], v[60:63]
	v_mfma_f32_16x16x32_bf16 v[56:59], v[184:187], v[208:211], v[56:59]
	v_mfma_f32_16x16x32_bf16 v[52:55], v[176:179], v[216:219], v[52:55]
	v_mfma_f32_16x16x32_bf16 v[44:47], v[184:187], v[216:219], v[44:47]
	v_mfma_f32_16x16x32_bf16 v[36:39], v[176:179], v[224:227], v[36:39]
	v_mfma_f32_16x16x32_bf16 v[28:31], v[184:187], v[224:227], v[28:31]
	v_mfma_f32_16x16x32_bf16 v[20:23], v[176:179], v[232:235], v[20:23]
	v_mfma_f32_16x16x32_bf16 v[12:15], v[184:187], v[232:235], v[12:15]
	v_mfma_f32_16x16x32_bf16 v[60:63], v[180:183], v[212:215], v[60:63]
	v_mfma_f32_16x16x32_bf16 v[56:59], v[188:191], v[212:215], v[56:59]
	v_mfma_f32_16x16x32_bf16 v[52:55], v[180:183], v[220:223], v[52:55]
	v_mfma_f32_16x16x32_bf16 v[44:47], v[188:191], v[220:223], v[44:47]
	v_mfma_f32_16x16x32_bf16 v[36:39], v[180:183], v[228:231], v[36:39]
	v_mfma_f32_16x16x32_bf16 v[28:31], v[188:191], v[228:231], v[28:31]
	v_mfma_f32_16x16x32_bf16 v[20:23], v[180:183], v[236:239], v[20:23]
	v_mfma_f32_16x16x32_bf16 v[12:15], v[188:191], v[236:239], v[12:15]
	v_mfma_f32_16x16x32_bf16 v[48:51], v[192:195], v[208:211], v[48:51]
	v_mfma_f32_16x16x32_bf16 v[40:43], v[200:203], v[208:211], v[40:43]
	v_mfma_f32_16x16x32_bf16 v[32:35], v[192:195], v[216:219], v[32:35]
	v_mfma_f32_16x16x32_bf16 v[24:27], v[200:203], v[216:219], v[24:27]
	v_mfma_f32_16x16x32_bf16 v[16:19], v[192:195], v[224:227], v[16:19]
	v_mfma_f32_16x16x32_bf16 v[8:11], v[200:203], v[224:227], v[8:11]
	v_mfma_f32_16x16x32_bf16 v[4:7], v[192:195], v[232:235], v[4:7]
	v_mfma_f32_16x16x32_bf16 v[0:3], v[200:203], v[232:235], v[0:3]
	v_mfma_f32_16x16x32_bf16 v[48:51], v[196:199], v[212:215], v[48:51]
	v_mfma_f32_16x16x32_bf16 v[40:43], v[204:207], v[212:215], v[40:43]
	v_mfma_f32_16x16x32_bf16 v[32:35], v[196:199], v[220:223], v[32:35]
	v_mfma_f32_16x16x32_bf16 v[24:27], v[204:207], v[220:223], v[24:27]
	v_mfma_f32_16x16x32_bf16 v[16:19], v[196:199], v[228:231], v[16:19]
	v_mfma_f32_16x16x32_bf16 v[8:11], v[204:207], v[228:231], v[8:11]
	v_mfma_f32_16x16x32_bf16 v[4:7], v[196:199], v[236:239], v[4:7]
	v_mfma_f32_16x16x32_bf16 v[0:3], v[204:207], v[236:239], v[0:3]
	s_barrier
; #define PG8_STAGE(bufoff, gbase, voff) do { _Pragma("unroll") for (int _i = 0; _i < 2; ++_i) \
;         __builtin_amdgcn_global_load_lds((const unsigned*)((const char*)(gbase) + (voff)[_i]), (PG8_LAS unsigned*)(lds + (bufoff) + ldsw + _i * 8192), 16, 0, 0); } while (0)
; #define PG8_LDA(dst, b, h) do { _Pragma("unroll") for (int m = 0; m < 4; ++m) _Pragma("unroll") for (int k = 0; k < 2; ++k) dst[m][k] = *(const PG8_LAS bf16x8*)(lds + PG8_SA(b, h) + aoff + m * 2048 + k * 1024); } while (0)
; #define PG8_LDB(dst, b, h) do { _Pragma("unroll") for (int n = 0; n < 2; ++n) _Pragma("unroll") for (int k = 0; k < 2; ++k) dst[n][k] = *(const PG8_LAS bf16x8*)(lds + PG8_SB(b, h) + boff + n * 2048 + k * 1024); } while (0)
; #define PG8_MMA(ai, bj, At, Bt) do { __builtin_amdgcn_s_setprio(1); _Pragma("unroll") for (int m = 0; m < 4; ++m) _Pragma("unroll") for (int n = 0; n < 2; ++n) _Pragma("unroll") for (int k = 0; k < 2; ++k) \
;         acc[ai][bj][m][n] = __builtin_amdgcn_mfma_f32_16x16x32_bf16(Bt[n][k], At[m][k], acc[ai][bj][m][n], 0, 0, 0); __builtin_amdgcn_s_setprio(0); } while (0)
; #define PG8_WAIT_V(n) asm volatile("s_waitcnt vmcnt(" #n ")" ::: "memory")
; #define PG8_WAIT_L(n) asm volatile("s_waitcnt lgkmcnt(" #n ")" ::: "memory")
; #define PG8_BAR __builtin_amdgcn_s_barrier()
; #define PG8_SCHED __builtin_amdgcn_sched_barrier(0)
; template <class Epi, class Sched, bool ALIGN_EPI = false, bool SP2 = false>
; __device__ __forceinline__ void gemm_phase(PG8_LAS unsigned char* lds, const Gemm g, const Sched& S, const Epi& E, int tid_in) {
;     ...
;             PG8_LDB(B0, 1, 0); PG8_LDB(B1, 1, 1); PG8_SCHED; PG8_LDA(At, 1, 0); PG8_STAGE(PG8_SA(0, 1), a2 + hstep, voffA);
;             PG8_WAIT_V(8); PG8_WAIT_L(0); PG8_BAR; PG8_MMA(0, 0, At, B0); PG8_MMA(0, 1, At, B1); PG8_BAR; PG8_SCHED;
	s_setprio 1
	s_add_i32 s3, 0, 0x18000
	s_add_i32 s13, 0, 0x1c000
	v_add_u32_e32 v188, s3, v168
	v_add_u32_e32 v204, s13, v168
	ds_read_b128 v[176:179], v188
	ds_read_b128 v[180:183], v188 offset:1024
	ds_read_b128 v[184:187], v188 offset:2048
	ds_read_b128 v[188:191], v188 offset:3072
	ds_read_b128 v[192:195], v204
	ds_read_b128 v[196:199], v204 offset:1024
	ds_read_b128 v[200:203], v204 offset:2048
	ds_read_b128 v[204:207], v204 offset:3072
	v_lshl_add_u64 v[240:241], v[240:241], 0, s[98:99]
	s_mov_b32 m0, s18
	v_lshl_add_u64 v[252:253], v[240:241], 0, v[148:149]
	ds_read_b128 v[208:211], v175 offset:32768
	ds_read_b128 v[212:215], v175 offset:33792
	ds_read_b128 v[216:219], v175 offset:34816
	ds_read_b128 v[220:223], v175 offset:35840
	ds_read_b128 v[224:227], v175 offset:36864
	ds_read_b128 v[228:231], v175 offset:37888
	ds_read_b128 v[232:235], v175 offset:38912
	ds_read_b128 v[236:239], v175 offset:39936
	global_load_lds_dwordx4 v[252:253], off
	v_lshl_add_u64 v[240:241], v[240:241], 0, v[146:147]
	s_mov_b32 m0, s19
	s_nop 0
	global_load_lds_dwordx4 v[240:241], off
	s_setprio 0
	s_waitcnt vmcnt(8) lgkmcnt(0)
	s_barrier
	v_mfma_f32_16x16x32_bf16 v[124:127], v[176:179], v[208:211], v[124:127]
	v_mfma_f32_16x16x32_bf16 v[120:123], v[184:187], v[208:211], v[120:123]
	v_mfma_f32_16x16x32_bf16 v[116:119], v[176:179], v[216:219], v[116:119]
	v_mfma_f32_16x16x32_bf16 v[108:111], v[184:187], v[216:219], v[108:111]
	v_mfma_f32_16x16x32_bf16 v[100:103], v[176:179], v[224:227], v[100:103]
	v_mfma_f32_16x16x32_bf16 v[92:95], v[184:187], v[224:227], v[92:95]
	v_mfma_f32_16x16x32_bf16 v[84:87], v[176:179], v[232:235], v[84:87]
	v_mfma_f32_16x16x32_bf16 v[76:79], v[184:187], v[232:235], v[76:79]
	v_mfma_f32_16x16x32_bf16 v[124:127], v[180:183], v[212:215], v[124:127]
	v_mfma_f32_16x16x32_bf16 v[120:123], v[188:191], v[212:215], v[120:123]
	v_mfma_f32_16x16x32_bf16 v[116:119], v[180:183], v[220:223], v[116:119]
	v_mfma_f32_16x16x32_bf16 v[108:111], v[188:191], v[220:223], v[108:111]
	v_mfma_f32_16x16x32_bf16 v[100:103], v[180:183], v[228:231], v[100:103]
	v_mfma_f32_16x16x32_bf16 v[92:95], v[188:191], v[228:231], v[92:95]
	v_mfma_f32_16x16x32_bf16 v[84:87], v[180:183], v[236:239], v[84:87]
	v_mfma_f32_16x16x32_bf16 v[76:79], v[188:191], v[236:239], v[76:79]
	v_mfma_f32_16x16x32_bf16 v[112:115], v[192:195], v[208:211], v[112:115]
	v_mfma_f32_16x16x32_bf16 v[104:107], v[200:203], v[208:211], v[104:107]
	v_mfma_f32_16x16x32_bf16 v[96:99], v[192:195], v[216:219], v[96:99]
	v_mfma_f32_16x16x32_bf16 v[88:91], v[200:203], v[216:219], v[88:91]
	v_mfma_f32_16x16x32_bf16 v[80:83], v[192:195], v[224:227], v[80:83]
	v_mfma_f32_16x16x32_bf16 v[72:75], v[200:203], v[224:227], v[72:75]
	v_mfma_f32_16x16x32_bf16 v[68:71], v[192:195], v[232:235], v[68:71]
	v_mfma_f32_16x16x32_bf16 v[64:67], v[200:203], v[232:235], v[64:67]
	v_mfma_f32_16x16x32_bf16 v[112:115], v[196:199], v[212:215], v[112:115]
	v_mfma_f32_16x16x32_bf16 v[104:107], v[204:207], v[212:215], v[104:107]
	v_mfma_f32_16x16x32_bf16 v[96:99], v[196:199], v[220:223], v[96:99]
	v_mfma_f32_16x16x32_bf16 v[88:91], v[204:207], v[220:223], v[88:91]
	v_mfma_f32_16x16x32_bf16 v[80:83], v[196:199], v[228:231], v[80:83]
	v_mfma_f32_16x16x32_bf16 v[72:75], v[204:207], v[228:231], v[72:75]
	v_mfma_f32_16x16x32_bf16 v[68:71], v[196:199], v[236:239], v[68:71]
	v_mfma_f32_16x16x32_bf16 v[64:67], v[204:207], v[236:239], v[64:67]
	s_barrier
; #define PG8_STAGE(bufoff, gbase, voff) do { _Pragma("unroll") for (int _i = 0; _i < 2; ++_i) \
;         __builtin_amdgcn_global_load_lds((const unsigned*)((const char*)(gbase) + (voff)[_i]), (PG8_LAS unsigned*)(lds + (bufoff) + ldsw + _i * 8192), 16, 0, 0); } while (0)
; #define PG8_LDA(dst, b, h) do { _Pragma("unroll") for (int m = 0; m < 4; ++m) _Pragma("unroll") for (int k = 0; k < 2; ++k) dst[m][k] = *(const PG8_LAS bf16x8*)(lds + PG8_SA(b, h) + aoff + m * 2048 + k * 1024); } while (0)
; #define PG8_MMA(ai, bj, At, Bt) do { __builtin_amdgcn_s_setprio(1); _Pragma("unroll") for (int m = 0; m < 4; ++m) _Pragma("unroll") for (int n = 0; n < 2; ++n) _Pragma("unroll") for (int k = 0; k < 2; ++k) \
;         acc[ai][bj][m][n] = __builtin_amdgcn_mfma_f32_16x16x32_bf16(Bt[n][k], At[m][k], acc[ai][bj][m][n], 0, 0, 0); __builtin_amdgcn_s_setprio(0); } while (0)
; #define PG8_WAIT_V(n) asm volatile("s_waitcnt vmcnt(" #n ")" ::: "memory")
; #define PG8_WAIT_L(n) asm volatile("s_waitcnt lgkmcnt(" #n ")" ::: "memory")
; #define PG8_BAR __builtin_amdgcn_s_barrier()
; #define PG8_SCHED __builtin_amdgcn_sched_barrier(0)
; template <class Epi, class Sched, bool ALIGN_EPI = false, bool SP2 = false>
; __device__ __forceinline__ void gemm_phase(PG8_LAS unsigned char* lds, const Gemm g, const Sched& S, const Epi& E, int tid_in) {
;     ...
;         for (int t = 0; t < nt; t += 2) {
;             const bool last = (t == nt - 2);
;     ...
;             PG8_LDA(At, 1, 1); PG8_STAGE(PG8_SB(1, 0), b3, voffB); PG8_STAGE(PG8_SB(1, 1), b3 + hstep, voffB); PG8_STAGE(PG8_SA(1, 0), a3, voffA);
;             PG8_WAIT_V(8); PG8_WAIT_L(0); PG8_BAR; PG8_MMA(1, 0, At, B0); PG8_MMA(1, 1, At, B1); PG8_BAR; PG8_SCHED;
	s_setprio 1
	s_add_i32 s3, s3, s1
	v_lshl_add_u64 v[240:241], v[244:245], 0, s[70:71]
	s_mov_b32 m0, s3
	ds_read_b128 v[208:211], v175 offset:49152
	ds_read_b128 v[212:215], v175 offset:50176
	ds_read_b128 v[216:219], v175 offset:51200
	ds_read_b128 v[220:223], v175 offset:52224
	ds_read_b128 v[224:227], v175 offset:53248
	ds_read_b128 v[228:231], v175 offset:54272
	ds_read_b128 v[232:235], v175 offset:55296
	ds_read_b128 v[236:239], v175 offset:56320
	global_load_lds_dwordx4 v[240:241], off
	v_lshl_add_u64 v[240:241], v[246:247], 0, s[70:71]
	s_add_i32 m0, s3, 0x2000
	s_add_i32 s3, s13, s1
	global_load_lds_dwordx4 v[240:241], off
	v_lshl_add_u64 v[240:241], v[242:243], 0, s[86:87]
	v_lshl_add_u64 v[242:243], v[240:241], 0, v[128:129]
	s_mov_b32 m0, s3
	v_lshl_add_u64 v[240:241], v[240:241], 0, v[144:145]
	global_load_lds_dwordx4 v[242:243], off
	s_add_i32 m0, s3, 0x2000
	s_nop 0
	global_load_lds_dwordx4 v[240:241], off
	v_lshl_add_u64 v[240:241], v[248:249], 0, s[70:71]
	s_mov_b32 m0, s20
	s_nop 0
	global_load_lds_dwordx4 v[240:241], off
	v_lshl_add_u64 v[240:241], v[250:251], 0, s[70:71]
	s_mov_b32 m0, s21
	s_nop 0
	global_load_lds_dwordx4 v[240:241], off
	s_setprio 0
	s_waitcnt vmcnt(8) lgkmcnt(0)
	s_barrier
	v_mfma_f32_16x16x32_bf16 v[60:63], v[176:179], v[208:211], v[60:63]
	v_mfma_f32_16x16x32_bf16 v[56:59], v[184:187], v[208:211], v[56:59]
	v_mfma_f32_16x16x32_bf16 v[52:55], v[176:179], v[216:219], v[52:55]
	v_mfma_f32_16x16x32_bf16 v[44:47], v[184:187], v[216:219], v[44:47]
	v_mfma_f32_16x16x32_bf16 v[36:39], v[176:179], v[224:227], v[36:39]
	v_mfma_f32_16x16x32_bf16 v[28:31], v[184:187], v[224:227], v[28:31]
	v_mfma_f32_16x16x32_bf16 v[20:23], v[176:179], v[232:235], v[20:23]
	v_mfma_f32_16x16x32_bf16 v[12:15], v[184:187], v[232:235], v[12:15]
	v_mfma_f32_16x16x32_bf16 v[60:63], v[180:183], v[212:215], v[60:63]
	v_mfma_f32_16x16x32_bf16 v[56:59], v[188:191], v[212:215], v[56:59]
	v_mfma_f32_16x16x32_bf16 v[52:55], v[180:183], v[220:223], v[52:55]
	v_mfma_f32_16x16x32_bf16 v[44:47], v[188:191], v[220:223], v[44:47]
	v_mfma_f32_16x16x32_bf16 v[36:39], v[180:183], v[228:231], v[36:39]
	v_mfma_f32_16x16x32_bf16 v[28:31], v[188:191], v[228:231], v[28:31]
	v_mfma_f32_16x16x32_bf16 v[20:23], v[180:183], v[236:239], v[20:23]
	v_mfma_f32_16x16x32_bf16 v[12:15], v[188:191], v[236:239], v[12:15]
	v_mfma_f32_16x16x32_bf16 v[48:51], v[192:195], v[208:211], v[48:51]
	v_mfma_f32_16x16x32_bf16 v[40:43], v[200:203], v[208:211], v[40:43]
	v_mfma_f32_16x16x32_bf16 v[32:35], v[192:195], v[216:219], v[32:35]
	v_mfma_f32_16x16x32_bf16 v[24:27], v[200:203], v[216:219], v[24:27]
	v_mfma_f32_16x16x32_bf16 v[16:19], v[192:195], v[224:227], v[16:19]
	v_mfma_f32_16x16x32_bf16 v[8:11], v[200:203], v[224:227], v[8:11]
	v_mfma_f32_16x16x32_bf16 v[4:7], v[192:195], v[232:235], v[4:7]
	v_mfma_f32_16x16x32_bf16 v[0:3], v[200:203], v[232:235], v[0:3]
	v_mfma_f32_16x16x32_bf16 v[48:51], v[196:199], v[212:215], v[48:51]
	v_mfma_f32_16x16x32_bf16 v[40:43], v[204:207], v[212:215], v[40:43]
	v_mfma_f32_16x16x32_bf16 v[32:35], v[196:199], v[220:223], v[32:35]
	v_mfma_f32_16x16x32_bf16 v[24:27], v[204:207], v[220:223], v[24:27]
	v_mfma_f32_16x16x32_bf16 v[16:19], v[196:199], v[228:231], v[16:19]
	v_mfma_f32_16x16x32_bf16 v[8:11], v[204:207], v[228:231], v[8:11]
	v_mfma_f32_16x16x32_bf16 v[4:7], v[196:199], v[236:239], v[4:7]
	v_mfma_f32_16x16x32_bf16 v[0:3], v[204:207], v[236:239], v[0:3]
	s_barrier
	s_setprio 1
	s_add_i32 s2, s2, 2
	v_lshl_add_u64 v[164:165], v[164:165], 0, s[82:83]
	s_cmp_gt_u32 s2, 29
	v_lshl_add_u64 v[166:167], v[166:167], 0, s[82:83]
	s_cbranch_scc0 .LBB0_405
	s_setprio 0
	s_and_b64 vcc, exec, s[10:11]
	s_cbranch_vccz .LBB0_408
	s_barrier

; template <class Epi, class Sched, bool ALIGN_EPI = false, bool SP2 = false>
; __device__ __forceinline__ void gemm_phase(PG8_LAS unsigned char* lds, const Gemm g, const Sched& S, const Epi& E, int tid_in) {
;     ...
;         const char* nA = has_next ? (const char*)g.A + (size_t)nxt.pm * tstep : cA; const char* nB = has_next ? (const char*)g.Bt + (size_t)nxt.pn * tstep : cB;
;         for (int t = 0; t < nt; t += 2) {
;             const bool last = (t == nt - 2);
;             const char* a1 = cA + (size_t)(t + 1) * kstep;
;             const char* a2 = last ? nA : cA + (size_t)(t + 2) * kstep; const char* b2 = last ? nB : cB + (size_t)(t + 2) * kstep;
;             const char* a3 = a2 + kstep; const char* b3 = b2 + kstep;
;             if (last && has_next) S.a_ready(nxt);
;     ...
;         for (int a = 0; a < 2; ++a)
; #pragma unroll
;             for (int b = 0; b < 2; ++b)
; #pragma unroll
;                 for (int m = 0; m < 4; ++m)
; #pragma unroll
;                     for (int n = 0; n < 2; ++n) acc[a][b][m][n] = (f32x4){0.f, 0.f, 0.f, 0.f};
;         cur = nxt; cA = nA; cB = nB; ++ui;
.LBB0_587:
	s_ashr_i32 s13, s12, 31
	s_lshl_b64 s[2:3], s[12:13], 20
	s_ashr_i32 s11, s10, 31
	v_lshl_add_u64 v[156:157], v[140:141], 0, s[2:3]
	s_lshl_b64 s[2:3], s[10:11], 20
	v_lshl_add_u64 v[158:159], v[142:143], 0, s[2:3]
	v_cndmask_b32_e64 v162, v0, v158, s[4:5]
	v_lshl_add_u64 v[164:165], v[0:1], 0, s[82:83]
	v_mov_b32_e32 v0, 0
	v_cndmask_b32_e64 v131, v3, v157, s[4:5]
	v_cndmask_b32_e64 v160, v2, v156, s[4:5]
	v_cndmask_b32_e64 v161, v1, v159, s[4:5]
	v_lshl_add_u64 v[166:167], v[2:3], 0, s[86:87]
	s_mov_b32 s2, -2
	v_mov_b32_e32 v1, v0
	v_mov_b32_e32 v2, v0
	v_mov_b32_e32 v3, v0
	v_mov_b32_e32 v8, v0
	v_mov_b32_e32 v9, v0
	v_mov_b32_e32 v10, v0
	v_mov_b32_e32 v11, v0
	v_mov_b32_e32 v16, v0
	v_mov_b32_e32 v17, v0
	v_mov_b32_e32 v18, v0
	v_mov_b32_e32 v19, v0
	v_mov_b32_e32 v24, v0
	v_mov_b32_e32 v25, v0
	v_mov_b32_e32 v26, v0
	v_mov_b32_e32 v27, v0
	v_mov_b32_e32 v32, v0
	v_mov_b32_e32 v33, v0
	v_mov_b32_e32 v34, v0
	v_mov_b32_e32 v35, v0
	v_mov_b32_e32 v40, v0
	v_mov_b32_e32 v41, v0
	v_mov_b32_e32 v42, v0
	v_mov_b32_e32 v43, v0
	v_mov_b32_e32 v48, v0
	v_mov_b32_e32 v49, v0
	v_mov_b32_e32 v50, v0
	v_mov_b32_e32 v51, v0
	v_mov_b32_e32 v56, v0
	v_mov_b32_e32 v57, v0
	v_mov_b32_e32 v58, v0
	v_mov_b32_e32 v59, v0
	v_mov_b32_e32 v4, v0
	v_mov_b32_e32 v5, v0
	v_mov_b32_e32 v6, v0
	v_mov_b32_e32 v7, v0
	v_mov_b32_e32 v12, v0
	v_mov_b32_e32 v13, v0
	v_mov_b32_e32 v14, v0
	v_mov_b32_e32 v15, v0
	v_mov_b32_e32 v20, v0
	v_mov_b32_e32 v21, v0
	v_mov_b32_e32 v22, v0
	v_mov_b32_e32 v23, v0
	v_mov_b32_e32 v28, v0
	v_mov_b32_e32 v29, v0
	v_mov_b32_e32 v30, v0
	v_mov_b32_e32 v31, v0
	v_mov_b32_e32 v36, v0
	v_mov_b32_e32 v37, v0
	v_mov_b32_e32 v38, v0
	v_mov_b32_e32 v39, v0
	v_mov_b32_e32 v44, v0
	v_mov_b32_e32 v45, v0
	v_mov_b32_e32 v46, v0
	v_mov_b32_e32 v47, v0
	v_mov_b32_e32 v52, v0
	v_mov_b32_e32 v53, v0
	v_mov_b32_e32 v54, v0
	v_mov_b32_e32 v55, v0
	v_mov_b32_e32 v60, v0
	v_mov_b32_e32 v61, v0
	v_mov_b32_e32 v62, v0
	v_mov_b32_e32 v63, v0
	v_mov_b32_e32 v64, v0
	v_mov_b32_e32 v65, v0
	v_mov_b32_e32 v66, v0
	v_mov_b32_e32 v67, v0
	v_mov_b32_e32 v72, v0
	v_mov_b32_e32 v73, v0
	v_mov_b32_e32 v74, v0
	v_mov_b32_e32 v75, v0
	v_mov_b32_e32 v80, v0
	v_mov_b32_e32 v81, v0
	v_mov_b32_e32 v82, v0
	v_mov_b32_e32 v83, v0
	v_mov_b32_e32 v88, v0
	v_mov_b32_e32 v89, v0
	v_mov_b32_e32 v90, v0
	v_mov_b32_e32 v91, v0
	v_mov_b32_e32 v96, v0
	v_mov_b32_e32 v97, v0
	v_mov_b32_e32 v98, v0
	v_mov_b32_e32 v99, v0
	v_mov_b32_e32 v104, v0
	v_mov_b32_e32 v105, v0
	v_mov_b32_e32 v106, v0
	v_mov_b32_e32 v107, v0
	v_mov_b32_e32 v112, v0
	v_mov_b32_e32 v113, v0
	v_mov_b32_e32 v114, v0
	v_mov_b32_e32 v115, v0
	v_mov_b32_e32 v120, v0
	v_mov_b32_e32 v121, v0
	v_mov_b32_e32 v122, v0
	v_mov_b32_e32 v123, v0
	v_mov_b32_e32 v68, v0
	v_mov_b32_e32 v69, v0
	v_mov_b32_e32 v70, v0
	v_mov_b32_e32 v71, v0
	v_mov_b32_e32 v76, v0
	v_mov_b32_e32 v77, v0
	v_mov_b32_e32 v78, v0
	v_mov_b32_e32 v79, v0
	v_mov_b32_e32 v84, v0
	v_mov_b32_e32 v85, v0
	v_mov_b32_e32 v86, v0
	v_mov_b32_e32 v87, v0
	v_mov_b32_e32 v92, v0
	v_mov_b32_e32 v93, v0
	v_mov_b32_e32 v94, v0
	v_mov_b32_e32 v95, v0
	v_mov_b32_e32 v100, v0
	v_mov_b32_e32 v101, v0
	v_mov_b32_e32 v102, v0
	v_mov_b32_e32 v103, v0
	v_mov_b32_e32 v108, v0
	v_mov_b32_e32 v109, v0
	v_mov_b32_e32 v110, v0
	v_mov_b32_e32 v111, v0
	v_mov_b32_e32 v116, v0
	v_mov_b32_e32 v117, v0
	v_mov_b32_e32 v118, v0
	v_mov_b32_e32 v119, v0
	v_mov_b32_e32 v124, v0
	v_mov_b32_e32 v125, v0
	v_mov_b32_e32 v126, v0
	v_mov_b32_e32 v127, v0
	s_setprio 1
.LBB0_588:
	s_cmp_eq_u32 s2, 28
	s_cselect_b64 vcc, -1, 0
	s_add_i32 s3, 0, 0x10000
	s_add_i32 s11, 0, 0x14000
	v_lshl_add_u64 v[176:177], v[166:167], 0, s[52:53]
	v_add_u32_e32 v188, s3, v168
	v_add_u32_e32 v204, s11, v168
	v_cndmask_b32_e32 v241, v177, v131, vcc
	v_cndmask_b32_e32 v240, v176, v160, vcc
	ds_read_b128 v[176:179], v188
	ds_read_b128 v[180:183], v188 offset:1024
	ds_read_b128 v[184:187], v188 offset:2048
	ds_read_b128 v[188:191], v188 offset:3072
	ds_read_b128 v[192:195], v204
	ds_read_b128 v[196:199], v204 offset:1024
	ds_read_b128 v[200:203], v204 offset:2048
	ds_read_b128 v[204:207], v204 offset:3072
	v_cndmask_b32_e32 v243, v165, v161, vcc
	v_cndmask_b32_e32 v242, v164, v162, vcc
	v_lshl_add_u64 v[244:245], v[166:167], 0, v[154:155]
	s_add_i32 m0, s15, 0xc000
	ds_read_b128 v[208:211], v175
	ds_read_b128 v[212:215], v175 offset:1024
	ds_read_b128 v[216:219], v175 offset:2048
	ds_read_b128 v[220:223], v175 offset:3072
	ds_read_b128 v[224:227], v175 offset:4096
	ds_read_b128 v[228:231], v175 offset:5120
	ds_read_b128 v[232:235], v175 offset:6144
	ds_read_b128 v[236:239], v175 offset:7168
	global_load_lds_dwordx4 v[244:245], off
	v_lshl_add_u64 v[244:245], v[166:167], 0, v[152:153]
	s_add_i32 m0, s15, 0xe000
	s_nop 0
	global_load_lds_dwordx4 v[244:245], off
	s_setprio 0
	s_waitcnt vmcnt(8) lgkmcnt(0)
	s_barrier
; #define PG8_STAGE(bufoff, gbase, voff) do { _Pragma("unroll") for (int _i = 0; _i < 2; ++_i) \
;         __builtin_amdgcn_global_load_lds((const unsigned*)((const char*)(gbase) + (voff)[_i]), (PG8_LAS unsigned*)(lds + (bufoff) + ldsw + _i * 8192), 16, 0, 0); } while (0)
; #define PG8_LDA(dst, b, h) do { _Pragma("unroll") for (int m = 0; m < 4; ++m) _Pragma("unroll") for (int k = 0; k < 2; ++k) dst[m][k] = *(const PG8_LAS bf16x8*)(lds + PG8_SA(b, h) + aoff + m * 2048 + k * 1024); } while (0)
; #define PG8_MMA(ai, bj, At, Bt) do { __builtin_amdgcn_s_setprio(1); _Pragma("unroll") for (int m = 0; m < 4; ++m) _Pragma("unroll") for (int n = 0; n < 2; ++n) _Pragma("unroll") for (int k = 0; k < 2; ++k) \
;         acc[ai][bj][m][n] = __builtin_amdgcn_mfma_f32_16x16x32_bf16(Bt[n][k], At[m][k], acc[ai][bj][m][n], 0, 0, 0); __builtin_amdgcn_s_setprio(0); } while (0)
; #define PG8_WAIT_V(n) asm volatile("s_waitcnt vmcnt(" #n ")" ::: "memory")
; #define PG8_WAIT_L(n) asm volatile("s_waitcnt lgkmcnt(" #n ")" ::: "memory")
; #define PG8_BAR __builtin_amdgcn_s_barrier()
; #define PG8_SCHED __builtin_amdgcn_sched_barrier(0)
; template <class Epi, class Sched, bool ALIGN_EPI = false, bool SP2 = false>
; __device__ __forceinline__ void gemm_phase(PG8_LAS unsigned char* lds, const Gemm g, const Sched& S, const Epi& E, int tid_in) {
;     ...
;             PG8_WAIT_V(8); PG8_WAIT_L(0); PG8_BAR; PG8_MMA(0, 0, At, B0); PG8_MMA(0, 1, At, B1); PG8_BAR; PG8_SCHED;
;             PG8_LDA(At, 0, 1); PG8_STAGE(PG8_SB(0, 0), b2, voffB); PG8_STAGE(PG8_SB(0, 1), b2 + hstep, voffB); PG8_STAGE(PG8_SA(0, 0), a2, voffA);
;             PG8_WAIT_V(8); PG8_WAIT_L(0); PG8_BAR; PG8_MMA(1, 0, At, B0); PG8_MMA(1, 1, At, B1); PG8_BAR; PG8_SCHED;
	v_mfma_f32_16x16x32_bf16 v[124:127], v[176:179], v[208:211], v[124:127]
	v_mfma_f32_16x16x32_bf16 v[116:119], v[184:187], v[208:211], v[116:119]
	v_mfma_f32_16x16x32_bf16 v[108:111], v[176:179], v[216:219], v[108:111]
	v_mfma_f32_16x16x32_bf16 v[100:103], v[184:187], v[216:219], v[100:103]
	v_mfma_f32_16x16x32_bf16 v[92:95], v[176:179], v[224:227], v[92:95]
	v_mfma_f32_16x16x32_bf16 v[84:87], v[184:187], v[224:227], v[84:87]
	v_mfma_f32_16x16x32_bf16 v[76:79], v[176:179], v[232:235], v[76:79]
	v_mfma_f32_16x16x32_bf16 v[68:71], v[184:187], v[232:235], v[68:71]
	v_mfma_f32_16x16x32_bf16 v[124:127], v[180:183], v[212:215], v[124:127]
	v_mfma_f32_16x16x32_bf16 v[116:119], v[188:191], v[212:215], v[116:119]
	v_mfma_f32_16x16x32_bf16 v[108:111], v[180:183], v[220:223], v[108:111]
	v_mfma_f32_16x16x32_bf16 v[100:103], v[188:191], v[220:223], v[100:103]
	v_mfma_f32_16x16x32_bf16 v[92:95], v[180:183], v[228:231], v[92:95]
	v_mfma_f32_16x16x32_bf16 v[84:87], v[188:191], v[228:231], v[84:87]
	v_mfma_f32_16x16x32_bf16 v[76:79], v[180:183], v[236:239], v[76:79]
	v_mfma_f32_16x16x32_bf16 v[68:71], v[188:191], v[236:239], v[68:71]
	v_mfma_f32_16x16x32_bf16 v[120:123], v[192:195], v[208:211], v[120:123]
	v_mfma_f32_16x16x32_bf16 v[112:115], v[200:203], v[208:211], v[112:115]
	v_mfma_f32_16x16x32_bf16 v[104:107], v[192:195], v[216:219], v[104:107]
	v_mfma_f32_16x16x32_bf16 v[96:99], v[200:203], v[216:219], v[96:99]
	v_mfma_f32_16x16x32_bf16 v[88:91], v[192:195], v[224:227], v[88:91]
	v_mfma_f32_16x16x32_bf16 v[80:83], v[200:203], v[224:227], v[80:83]
	v_mfma_f32_16x16x32_bf16 v[72:75], v[192:195], v[232:235], v[72:75]
	v_mfma_f32_16x16x32_bf16 v[64:67], v[200:203], v[232:235], v[64:67]
	v_mfma_f32_16x16x32_bf16 v[120:123], v[196:199], v[212:215], v[120:123]
	v_mfma_f32_16x16x32_bf16 v[112:115], v[204:207], v[212:215], v[112:115]
	v_mfma_f32_16x16x32_bf16 v[104:107], v[196:199], v[220:223], v[104:107]
	v_mfma_f32_16x16x32_bf16 v[96:99], v[204:207], v[220:223], v[96:99]
	v_mfma_f32_16x16x32_bf16 v[88:91], v[196:199], v[228:231], v[88:91]
	v_mfma_f32_16x16x32_bf16 v[80:83], v[204:207], v[228:231], v[80:83]
	v_mfma_f32_16x16x32_bf16 v[72:75], v[196:199], v[236:239], v[72:75]
	v_mfma_f32_16x16x32_bf16 v[64:67], v[204:207], v[236:239], v[64:67]
	s_barrier
	s_setprio 1
	s_add_i32 s3, s3, s14
	v_lshl_add_u64 v[244:245], v[242:243], 0, v[128:129]
	s_mov_b32 m0, s3
	ds_read_b128 v[208:211], v175 offset:16384
	ds_read_b128 v[212:215], v175 offset:17408
	ds_read_b128 v[216:219], v175 offset:18432
	ds_read_b128 v[220:223], v175 offset:19456
	ds_read_b128 v[224:227], v175 offset:20480
	ds_read_b128 v[228:231], v175 offset:21504
	ds_read_b128 v[232:235], v175 offset:22528
	ds_read_b128 v[236:239], v175 offset:23552
	global_load_lds_dwordx4 v[244:245], off
	v_lshl_add_u64 v[246:247], v[242:243], 0, v[144:145]
	s_add_i32 m0, s3, 0x2000
	v_lshl_add_u64 v[248:249], v[242:243], 0, s[98:99]
	s_add_i32 s3, s11, s14
	global_load_lds_dwordx4 v[246:247], off
	v_lshl_add_u64 v[250:251], v[248:249], 0, v[128:129]
	s_mov_b32 m0, s3
	v_lshl_add_u64 v[248:249], v[248:249], 0, v[144:145]
	global_load_lds_dwordx4 v[250:251], off
	s_add_i32 m0, s3, 0x2000
	v_lshl_add_u64 v[250:251], v[240:241], 0, v[146:147]
	global_load_lds_dwordx4 v[248:249], off
	v_lshl_add_u64 v[248:249], v[240:241], 0, v[148:149]
	s_mov_b32 m0, s15
	s_nop 0
	global_load_lds_dwordx4 v[248:249], off
	s_mov_b32 m0, s16
	s_nop 0
	global_load_lds_dwordx4 v[250:251], off
	s_setprio 0
	s_waitcnt vmcnt(8) lgkmcnt(0)
	s_barrier
	v_mfma_f32_16x16x32_bf16 v[60:63], v[176:179], v[208:211], v[60:63]
	v_mfma_f32_16x16x32_bf16 v[52:55], v[184:187], v[208:211], v[52:55]
	v_mfma_f32_16x16x32_bf16 v[44:47], v[176:179], v[216:219], v[44:47]
	v_mfma_f32_16x16x32_bf16 v[36:39], v[184:187], v[216:219], v[36:39]
	v_mfma_f32_16x16x32_bf16 v[28:31], v[176:179], v[224:227], v[28:31]
	v_mfma_f32_16x16x32_bf16 v[20:23], v[184:187], v[224:227], v[20:23]
	v_mfma_f32_16x16x32_bf16 v[12:15], v[176:179], v[232:235], v[12:15]
	v_mfma_f32_16x16x32_bf16 v[4:7], v[184:187], v[232:235], v[4:7]
	v_mfma_f32_16x16x32_bf16 v[60:63], v[180:183], v[212:215], v[60:63]
	v_mfma_f32_16x16x32_bf16 v[52:55], v[188:191], v[212:215], v[52:55]
	v_mfma_f32_16x16x32_bf16 v[44:47], v[180:183], v[220:223], v[44:47]
	v_mfma_f32_16x16x32_bf16 v[36:39], v[188:191], v[220:223], v[36:39]
	v_mfma_f32_16x16x32_bf16 v[28:31], v[180:183], v[228:231], v[28:31]
	v_mfma_f32_16x16x32_bf16 v[20:23], v[188:191], v[228:231], v[20:23]
	v_mfma_f32_16x16x32_bf16 v[12:15], v[180:183], v[236:239], v[12:15]
	v_mfma_f32_16x16x32_bf16 v[4:7], v[188:191], v[236:239], v[4:7]
	v_mfma_f32_16x16x32_bf16 v[56:59], v[192:195], v[208:211], v[56:59]
	v_mfma_f32_16x16x32_bf16 v[48:51], v[200:203], v[208:211], v[48:51]
	v_mfma_f32_16x16x32_bf16 v[40:43], v[192:195], v[216:219], v[40:43]
	v_mfma_f32_16x16x32_bf16 v[32:35], v[200:203], v[216:219], v[32:35]
	v_mfma_f32_16x16x32_bf16 v[24:27], v[192:195], v[224:227], v[24:27]
	v_mfma_f32_16x16x32_bf16 v[16:19], v[200:203], v[224:227], v[16:19]
	v_mfma_f32_16x16x32_bf16 v[8:11], v[192:195], v[232:235], v[8:11]
	v_mfma_f32_16x16x32_bf16 v[0:3], v[200:203], v[232:235], v[0:3]
	v_mfma_f32_16x16x32_bf16 v[56:59], v[196:199], v[212:215], v[56:59]
	v_mfma_f32_16x16x32_bf16 v[48:51], v[204:207], v[212:215], v[48:51]
	v_mfma_f32_16x16x32_bf16 v[40:43], v[196:199], v[220:223], v[40:43]
	v_mfma_f32_16x16x32_bf16 v[32:35], v[204:207], v[220:223], v[32:35]
	v_mfma_f32_16x16x32_bf16 v[24:27], v[196:199], v[228:231], v[24:27]
	v_mfma_f32_16x16x32_bf16 v[16:19], v[204:207], v[228:231], v[16:19]
	v_mfma_f32_16x16x32_bf16 v[8:11], v[196:199], v[236:239], v[8:11]
	v_mfma_f32_16x16x32_bf16 v[0:3], v[204:207], v[236:239], v[0:3]
	s_barrier
; #define PG8_STAGE(bufoff, gbase, voff) do { _Pragma("unroll") for (int _i = 0; _i < 2; ++_i) \
;         __builtin_amdgcn_global_load_lds((const unsigned*)((const char*)(gbase) + (voff)[_i]), (PG8_LAS unsigned*)(lds + (bufoff) + ldsw + _i * 8192), 16, 0, 0); } while (0)
; #define PG8_LDA(dst, b, h) do { _Pragma("unroll") for (int m = 0; m < 4; ++m) _Pragma("unroll") for (int k = 0; k < 2; ++k) dst[m][k] = *(const PG8_LAS bf16x8*)(lds + PG8_SA(b, h) + aoff + m * 2048 + k * 1024); } while (0)
; #define PG8_LDB(dst, b, h) do { _Pragma("unroll") for (int n = 0; n < 2; ++n) _Pragma("unroll") for (int k = 0; k < 2; ++k) dst[n][k] = *(const PG8_LAS bf16x8*)(lds + PG8_SB(b, h) + boff + n * 2048 + k * 1024); } while (0)
; #define PG8_MMA(ai, bj, At, Bt) do { __builtin_amdgcn_s_setprio(1); _Pragma("unroll") for (int m = 0; m < 4; ++m) _Pragma("unroll") for (int n = 0; n < 2; ++n) _Pragma("unroll") for (int k = 0; k < 2; ++k) \
;         acc[ai][bj][m][n] = __builtin_amdgcn_mfma_f32_16x16x32_bf16(Bt[n][k], At[m][k], acc[ai][bj][m][n], 0, 0, 0); __builtin_amdgcn_s_setprio(0); } while (0)
; #define PG8_WAIT_V(n) asm volatile("s_waitcnt vmcnt(" #n ")" ::: "memory")
; #define PG8_WAIT_L(n) asm volatile("s_waitcnt lgkmcnt(" #n ")" ::: "memory")
; #define PG8_BAR __builtin_amdgcn_s_barrier()
; #define PG8_SCHED __builtin_amdgcn_sched_barrier(0)
; template <class Epi, class Sched, bool ALIGN_EPI = false, bool SP2 = false>
; __device__ __forceinline__ void gemm_phase(PG8_LAS unsigned char* lds, const Gemm g, const Sched& S, const Epi& E, int tid_in) {
;     ...
;             PG8_LDB(B0, 1, 0); PG8_LDB(B1, 1, 1); PG8_SCHED; PG8_LDA(At, 1, 0); PG8_STAGE(PG8_SA(0, 1), a2 + hstep, voffA);
;             PG8_WAIT_V(8); PG8_WAIT_L(0); PG8_BAR; PG8_MMA(0, 0, At, B0); PG8_MMA(0, 1, At, B1); PG8_BAR; PG8_SCHED;
	s_setprio 1
	s_add_i32 s3, 0, 0x18000
	s_add_i32 s11, 0, 0x1c000
	v_add_u32_e32 v188, s3, v168
	v_add_u32_e32 v204, s11, v168
	ds_read_b128 v[176:179], v188
	ds_read_b128 v[180:183], v188 offset:1024
	ds_read_b128 v[184:187], v188 offset:2048
	ds_read_b128 v[188:191], v188 offset:3072
	ds_read_b128 v[192:195], v204
	ds_read_b128 v[196:199], v204 offset:1024
	ds_read_b128 v[200:203], v204 offset:2048
	ds_read_b128 v[204:207], v204 offset:3072
	v_lshl_add_u64 v[240:241], v[240:241], 0, s[98:99]
	s_mov_b32 m0, s17
	v_lshl_add_u64 v[252:253], v[240:241], 0, v[148:149]
	ds_read_b128 v[208:211], v175 offset:32768
	ds_read_b128 v[212:215], v175 offset:33792
	ds_read_b128 v[216:219], v175 offset:34816
	ds_read_b128 v[220:223], v175 offset:35840
	ds_read_b128 v[224:227], v175 offset:36864
	ds_read_b128 v[228:231], v175 offset:37888
	ds_read_b128 v[232:235], v175 offset:38912
	ds_read_b128 v[236:239], v175 offset:39936
	global_load_lds_dwordx4 v[252:253], off
	v_lshl_add_u64 v[240:241], v[240:241], 0, v[146:147]
	s_mov_b32 m0, s18
	s_nop 0
	global_load_lds_dwordx4 v[240:241], off
	s_setprio 0
	s_waitcnt vmcnt(8) lgkmcnt(0)
	s_barrier
	v_mfma_f32_16x16x32_bf16 v[124:127], v[176:179], v[208:211], v[124:127]
	v_mfma_f32_16x16x32_bf16 v[116:119], v[184:187], v[208:211], v[116:119]
	v_mfma_f32_16x16x32_bf16 v[108:111], v[176:179], v[216:219], v[108:111]
	v_mfma_f32_16x16x32_bf16 v[100:103], v[184:187], v[216:219], v[100:103]
	v_mfma_f32_16x16x32_bf16 v[92:95], v[176:179], v[224:227], v[92:95]
	v_mfma_f32_16x16x32_bf16 v[84:87], v[184:187], v[224:227], v[84:87]
	v_mfma_f32_16x16x32_bf16 v[76:79], v[176:179], v[232:235], v[76:79]
	v_mfma_f32_16x16x32_bf16 v[68:71], v[184:187], v[232:235], v[68:71]
	v_mfma_f32_16x16x32_bf16 v[124:127], v[180:183], v[212:215], v[124:127]
	v_mfma_f32_16x16x32_bf16 v[116:119], v[188:191], v[212:215], v[116:119]
	v_mfma_f32_16x16x32_bf16 v[108:111], v[180:183], v[220:223], v[108:111]
	v_mfma_f32_16x16x32_bf16 v[100:103], v[188:191], v[220:223], v[100:103]
	v_mfma_f32_16x16x32_bf16 v[92:95], v[180:183], v[228:231], v[92:95]
	v_mfma_f32_16x16x32_bf16 v[84:87], v[188:191], v[228:231], v[84:87]
	v_mfma_f32_16x16x32_bf16 v[76:79], v[180:183], v[236:239], v[76:79]
	v_mfma_f32_16x16x32_bf16 v[68:71], v[188:191], v[236:239], v[68:71]
	v_mfma_f32_16x16x32_bf16 v[120:123], v[192:195], v[208:211], v[120:123]
	v_mfma_f32_16x16x32_bf16 v[112:115], v[200:203], v[208:211], v[112:115]
	v_mfma_f32_16x16x32_bf16 v[104:107], v[192:195], v[216:219], v[104:107]
	v_mfma_f32_16x16x32_bf16 v[96:99], v[200:203], v[216:219], v[96:99]
	v_mfma_f32_16x16x32_bf16 v[88:91], v[192:195], v[224:227], v[88:91]
	v_mfma_f32_16x16x32_bf16 v[80:83], v[200:203], v[224:227], v[80:83]
	v_mfma_f32_16x16x32_bf16 v[72:75], v[192:195], v[232:235], v[72:75]
	v_mfma_f32_16x16x32_bf16 v[64:67], v[200:203], v[232:235], v[64:67]
	v_mfma_f32_16x16x32_bf16 v[120:123], v[196:199], v[212:215], v[120:123]
	v_mfma_f32_16x16x32_bf16 v[112:115], v[204:207], v[212:215], v[112:115]
	v_mfma_f32_16x16x32_bf16 v[104:107], v[196:199], v[220:223], v[104:107]
	v_mfma_f32_16x16x32_bf16 v[96:99], v[204:207], v[220:223], v[96:99]
	v_mfma_f32_16x16x32_bf16 v[88:91], v[196:199], v[228:231], v[88:91]
	v_mfma_f32_16x16x32_bf16 v[80:83], v[204:207], v[228:231], v[80:83]
	v_mfma_f32_16x16x32_bf16 v[72:75], v[196:199], v[236:239], v[72:75]
	v_mfma_f32_16x16x32_bf16 v[64:67], v[204:207], v[236:239], v[64:67]
	s_barrier
; #define PG8_STAGE(bufoff, gbase, voff) do { _Pragma("unroll") for (int _i = 0; _i < 2; ++_i) \
;         __builtin_amdgcn_global_load_lds((const unsigned*)((const char*)(gbase) + (voff)[_i]), (PG8_LAS unsigned*)(lds + (bufoff) + ldsw + _i * 8192), 16, 0, 0); } while (0)
; #define PG8_LDA(dst, b, h) do { _Pragma("unroll") for (int m = 0; m < 4; ++m) _Pragma("unroll") for (int k = 0; k < 2; ++k) dst[m][k] = *(const PG8_LAS bf16x8*)(lds + PG8_SA(b, h) + aoff + m * 2048 + k * 1024); } while (0)
; #define PG8_MMA(ai, bj, At, Bt) do { __builtin_amdgcn_s_setprio(1); _Pragma("unroll") for (int m = 0; m < 4; ++m) _Pragma("unroll") for (int n = 0; n < 2; ++n) _Pragma("unroll") for (int k = 0; k < 2; ++k) \
;         acc[ai][bj][m][n] = __builtin_amdgcn_mfma_f32_16x16x32_bf16(Bt[n][k], At[m][k], acc[ai][bj][m][n], 0, 0, 0); __builtin_amdgcn_s_setprio(0); } while (0)
; #define PG8_WAIT_V(n) asm volatile("s_waitcnt vmcnt(" #n ")" ::: "memory")
; #define PG8_WAIT_L(n) asm volatile("s_waitcnt lgkmcnt(" #n ")" ::: "memory")
; #define PG8_BAR __builtin_amdgcn_s_barrier()
; #define PG8_SCHED __builtin_amdgcn_sched_barrier(0)
; template <class Epi, class Sched, bool ALIGN_EPI = false, bool SP2 = false>
; __device__ __forceinline__ void gemm_phase(PG8_LAS unsigned char* lds, const Gemm g, const Sched& S, const Epi& E, int tid_in) {
;     ...
;         for (int t = 0; t < nt; t += 2) {
;             const bool last = (t == nt - 2);
;     ...
;             PG8_LDA(At, 1, 1); PG8_STAGE(PG8_SB(1, 0), b3, voffB); PG8_STAGE(PG8_SB(1, 1), b3 + hstep, voffB); PG8_STAGE(PG8_SA(1, 0), a3, voffA);
;             PG8_WAIT_V(8); PG8_WAIT_L(0); PG8_BAR; PG8_MMA(1, 0, At, B0); PG8_MMA(1, 1, At, B1); PG8_BAR; PG8_SCHED;
	s_setprio 1
	s_add_i32 s3, s3, s14
	v_lshl_add_u64 v[240:241], v[244:245], 0, s[70:71]
	s_mov_b32 m0, s3
	ds_read_b128 v[208:211], v175 offset:49152
	ds_read_b128 v[212:215], v175 offset:50176
	ds_read_b128 v[216:219], v175 offset:51200
	ds_read_b128 v[220:223], v175 offset:52224
	ds_read_b128 v[224:227], v175 offset:53248
	ds_read_b128 v[228:231], v175 offset:54272
	ds_read_b128 v[232:235], v175 offset:55296
	ds_read_b128 v[236:239], v175 offset:56320
	global_load_lds_dwordx4 v[240:241], off
	v_lshl_add_u64 v[240:241], v[246:247], 0, s[70:71]
	s_add_i32 m0, s3, 0x2000
	s_add_i32 s3, s11, s14
	global_load_lds_dwordx4 v[240:241], off
	v_lshl_add_u64 v[240:241], v[242:243], 0, s[86:87]
	v_lshl_add_u64 v[242:243], v[240:241], 0, v[128:129]
	s_mov_b32 m0, s3
	v_lshl_add_u64 v[240:241], v[240:241], 0, v[144:145]
	global_load_lds_dwordx4 v[242:243], off
	s_add_i32 m0, s3, 0x2000
	s_nop 0
	global_load_lds_dwordx4 v[240:241], off
	v_lshl_add_u64 v[240:241], v[248:249], 0, s[70:71]
	s_mov_b32 m0, s19
	s_nop 0
	global_load_lds_dwordx4 v[240:241], off
	v_lshl_add_u64 v[240:241], v[250:251], 0, s[70:71]
	s_mov_b32 m0, s1
	s_nop 0
	global_load_lds_dwordx4 v[240:241], off
	s_setprio 0
	s_waitcnt vmcnt(8) lgkmcnt(0)
	s_barrier
	v_mfma_f32_16x16x32_bf16 v[60:63], v[176:179], v[208:211], v[60:63]
	v_mfma_f32_16x16x32_bf16 v[52:55], v[184:187], v[208:211], v[52:55]
	v_mfma_f32_16x16x32_bf16 v[44:47], v[176:179], v[216:219], v[44:47]
	v_mfma_f32_16x16x32_bf16 v[36:39], v[184:187], v[216:219], v[36:39]
	v_mfma_f32_16x16x32_bf16 v[28:31], v[176:179], v[224:227], v[28:31]
	v_mfma_f32_16x16x32_bf16 v[20:23], v[184:187], v[224:227], v[20:23]
	v_mfma_f32_16x16x32_bf16 v[12:15], v[176:179], v[232:235], v[12:15]
	v_mfma_f32_16x16x32_bf16 v[4:7], v[184:187], v[232:235], v[4:7]
	v_mfma_f32_16x16x32_bf16 v[60:63], v[180:183], v[212:215], v[60:63]
	v_mfma_f32_16x16x32_bf16 v[52:55], v[188:191], v[212:215], v[52:55]
	v_mfma_f32_16x16x32_bf16 v[44:47], v[180:183], v[220:223], v[44:47]
	v_mfma_f32_16x16x32_bf16 v[36:39], v[188:191], v[220:223], v[36:39]
	v_mfma_f32_16x16x32_bf16 v[28:31], v[180:183], v[228:231], v[28:31]
	v_mfma_f32_16x16x32_bf16 v[20:23], v[188:191], v[228:231], v[20:23]
	v_mfma_f32_16x16x32_bf16 v[12:15], v[180:183], v[236:239], v[12:15]
	v_mfma_f32_16x16x32_bf16 v[4:7], v[188:191], v[236:239], v[4:7]
	v_mfma_f32_16x16x32_bf16 v[56:59], v[192:195], v[208:211], v[56:59]
	v_mfma_f32_16x16x32_bf16 v[48:51], v[200:203], v[208:211], v[48:51]
	v_mfma_f32_16x16x32_bf16 v[40:43], v[192:195], v[216:219], v[40:43]
	v_mfma_f32_16x16x32_bf16 v[32:35], v[200:203], v[216:219], v[32:35]
	v_mfma_f32_16x16x32_bf16 v[24:27], v[192:195], v[224:227], v[24:27]
	v_mfma_f32_16x16x32_bf16 v[16:19], v[200:203], v[224:227], v[16:19]
	v_mfma_f32_16x16x32_bf16 v[8:11], v[192:195], v[232:235], v[8:11]
	v_mfma_f32_16x16x32_bf16 v[0:3], v[200:203], v[232:235], v[0:3]
	v_mfma_f32_16x16x32_bf16 v[56:59], v[196:199], v[212:215], v[56:59]
	v_mfma_f32_16x16x32_bf16 v[48:51], v[204:207], v[212:215], v[48:51]
	v_mfma_f32_16x16x32_bf16 v[40:43], v[196:199], v[220:223], v[40:43]
	v_mfma_f32_16x16x32_bf16 v[32:35], v[204:207], v[220:223], v[32:35]
	v_mfma_f32_16x16x32_bf16 v[24:27], v[196:199], v[228:231], v[24:27]
	v_mfma_f32_16x16x32_bf16 v[16:19], v[204:207], v[228:231], v[16:19]
	v_mfma_f32_16x16x32_bf16 v[8:11], v[196:199], v[236:239], v[8:11]
	v_mfma_f32_16x16x32_bf16 v[0:3], v[204:207], v[236:239], v[0:3]
	s_barrier
	s_setprio 1
	s_add_i32 s2, s2, 2
	v_lshl_add_u64 v[164:165], v[164:165], 0, s[82:83]
	s_cmp_gt_u32 s2, 29
	v_lshl_add_u64 v[166:167], v[166:167], 0, s[82:83]
	s_cbranch_scc0 .LBB0_588
	s_setprio 0
	s_and_b64 vcc, exec, s[8:9]
	s_cbranch_vccz .LBB0_591
	s_barrier

; #define PG8_STAGE(bufoff, gbase, voff) do { _Pragma("unroll") for (int _i = 0; _i < 2; ++_i) \
;         __builtin_amdgcn_global_load_lds((const unsigned*)((const char*)(gbase) + (voff)[_i]), (PG8_LAS unsigned*)(lds + (bufoff) + ldsw + _i * 8192), 16, 0, 0); } while (0)
; #define PG8_LDA(dst, b, h) do { _Pragma("unroll") for (int m = 0; m < 4; ++m) _Pragma("unroll") for (int k = 0; k < 2; ++k) dst[m][k] = *(const PG8_LAS bf16x8*)(lds + PG8_SA(b, h) + aoff + m * 2048 + k * 1024); } while (0)
; #define PG8_LDB(dst, b, h) do { _Pragma("unroll") for (int n = 0; n < 2; ++n) _Pragma("unroll") for (int k = 0; k < 2; ++k) dst[n][k] = *(const PG8_LAS bf16x8*)(lds + PG8_SB(b, h) + boff + n * 2048 + k * 1024); } while (0)
; #define PG8_WAIT_V(n) asm volatile("s_waitcnt vmcnt(" #n ")" ::: "memory")
; #define PG8_WAIT_L(n) asm volatile("s_waitcnt lgkmcnt(" #n ")" ::: "memory")
; #define PG8_BAR __builtin_amdgcn_s_barrier()
; #define PG8_SCHED __builtin_amdgcn_sched_barrier(0)
; template <class Epi, class Sched, bool ALIGN_EPI = false, bool SP2 = false>
; __device__ __forceinline__ void gemm_phase(PG8_LAS unsigned char* lds, const Gemm g, const Sched& S, const Epi& E, int tid_in) {
;     ...
;         const char* nA = has_next ? (const char*)g.A + (size_t)nxt.pm * tstep : cA; const char* nB = has_next ? (const char*)g.Bt + (size_t)nxt.pn * tstep : cB;
;         for (int t = 0; t < nt; t += 2) {
;             const bool last = (t == nt - 2);
;             const char* a1 = cA + (size_t)(t + 1) * kstep;
;             const char* a2 = last ? nA : cA + (size_t)(t + 2) * kstep; const char* b2 = last ? nB : cB + (size_t)(t + 2) * kstep;
;             const char* a3 = a2 + kstep; const char* b3 = b2 + kstep;
;             if (last && has_next) S.a_ready(nxt);
;             if constexpr (SP2) {
;             PG8_LDB(B0, 0, 0); PG8_LDB(B1, 0, 1); PG8_SCHED; PG8_LDA(At, 0, 0); PG8_STAGE(PG8_SA(1, 1), a1 + hstep, voffA);
;             PG8_WAIT_V(8); PG8_WAIT_L(0); PG8_BAR; PG8_MMA(0, 0, At, B0); PG8_MMA(0, 1, At, B1); PG8_BAR; PG8_SCHED;
;     ...
;         for (int a = 0; a < 2; ++a)
; #pragma unroll
;             for (int b = 0; b < 2; ++b)
; #pragma unroll
;                 for (int m = 0; m < 4; ++m)
; #pragma unroll
;                     for (int n = 0; n < 2; ++n) acc[a][b][m][n] = (f32x4){0.f, 0.f, 0.f, 0.f};
;         cur = nxt; cA = nA; cB = nB; ++ui;
.LBB0_682:
	v_lshl_add_u64 v[160:161], v[0:1], 0, s[82:83]
	v_mov_b32_e32 v0, 0
	s_mov_b32 s2, -2
	v_mov_b32_e32 v1, v0
	v_mov_b32_e32 v2, v0
	v_mov_b32_e32 v3, v0
	v_mov_b32_e32 v4, v0
	v_mov_b32_e32 v5, v0
	v_mov_b32_e32 v6, v0
	v_mov_b32_e32 v7, v0
	v_mov_b32_e32 v8, v0
	v_mov_b32_e32 v9, v0
	v_mov_b32_e32 v10, v0
	v_mov_b32_e32 v11, v0
	v_mov_b32_e32 v16, v0
	v_mov_b32_e32 v17, v0
	v_mov_b32_e32 v18, v0
	v_mov_b32_e32 v19, v0
	v_mov_b32_e32 v24, v0
	v_mov_b32_e32 v25, v0
	v_mov_b32_e32 v26, v0
	v_mov_b32_e32 v27, v0
	v_mov_b32_e32 v32, v0
	v_mov_b32_e32 v33, v0
	v_mov_b32_e32 v34, v0
	v_mov_b32_e32 v35, v0
	v_mov_b32_e32 v40, v0
	v_mov_b32_e32 v41, v0
	v_mov_b32_e32 v42, v0
	v_mov_b32_e32 v43, v0
	v_mov_b32_e32 v48, v0
	v_mov_b32_e32 v49, v0
	v_mov_b32_e32 v50, v0
	v_mov_b32_e32 v51, v0
	v_mov_b32_e32 v12, v0
	v_mov_b32_e32 v13, v0
	v_mov_b32_e32 v14, v0
	v_mov_b32_e32 v15, v0
	v_mov_b32_e32 v20, v0
	v_mov_b32_e32 v21, v0
	v_mov_b32_e32 v22, v0
	v_mov_b32_e32 v23, v0
	v_mov_b32_e32 v28, v0
	v_mov_b32_e32 v29, v0
	v_mov_b32_e32 v30, v0
	v_mov_b32_e32 v31, v0
	v_mov_b32_e32 v36, v0
	v_mov_b32_e32 v37, v0
	v_mov_b32_e32 v38, v0
	v_mov_b32_e32 v39, v0
	v_mov_b32_e32 v44, v0
	v_mov_b32_e32 v45, v0
	v_mov_b32_e32 v46, v0
	v_mov_b32_e32 v47, v0
	v_mov_b32_e32 v52, v0
	v_mov_b32_e32 v53, v0
	v_mov_b32_e32 v54, v0
	v_mov_b32_e32 v55, v0
	v_mov_b32_e32 v56, v0
	v_mov_b32_e32 v57, v0
	v_mov_b32_e32 v58, v0
	v_mov_b32_e32 v59, v0
	v_mov_b32_e32 v60, v0
	v_mov_b32_e32 v61, v0
	v_mov_b32_e32 v62, v0
	v_mov_b32_e32 v63, v0
	v_mov_b32_e32 v64, v0
	v_mov_b32_e32 v65, v0
	v_mov_b32_e32 v66, v0
	v_mov_b32_e32 v67, v0
	v_mov_b32_e32 v68, v0
	v_mov_b32_e32 v69, v0
	v_mov_b32_e32 v70, v0
	v_mov_b32_e32 v71, v0
	v_mov_b32_e32 v72, v0
	v_mov_b32_e32 v73, v0
	v_mov_b32_e32 v74, v0
	v_mov_b32_e32 v75, v0
	v_mov_b32_e32 v80, v0
	v_mov_b32_e32 v81, v0
	v_mov_b32_e32 v82, v0
	v_mov_b32_e32 v83, v0
	v_mov_b32_e32 v88, v0
	v_mov_b32_e32 v89, v0
	v_mov_b32_e32 v90, v0
	v_mov_b32_e32 v91, v0
	v_mov_b32_e32 v96, v0
	v_mov_b32_e32 v97, v0
	v_mov_b32_e32 v98, v0
	v_mov_b32_e32 v99, v0
	v_mov_b32_e32 v104, v0
	v_mov_b32_e32 v105, v0
	v_mov_b32_e32 v106, v0
	v_mov_b32_e32 v107, v0
	v_mov_b32_e32 v112, v0
	v_mov_b32_e32 v113, v0
	v_mov_b32_e32 v114, v0
	v_mov_b32_e32 v115, v0
	v_mov_b32_e32 v76, v0
	v_mov_b32_e32 v77, v0
	v_mov_b32_e32 v78, v0
	v_mov_b32_e32 v79, v0
	v_mov_b32_e32 v84, v0
	v_mov_b32_e32 v85, v0
	v_mov_b32_e32 v86, v0
	v_mov_b32_e32 v87, v0
	v_mov_b32_e32 v92, v0
	v_mov_b32_e32 v93, v0
	v_mov_b32_e32 v94, v0
	v_mov_b32_e32 v95, v0
	v_mov_b32_e32 v100, v0
	v_mov_b32_e32 v101, v0
	v_mov_b32_e32 v102, v0
	v_mov_b32_e32 v103, v0
	v_mov_b32_e32 v108, v0
	v_mov_b32_e32 v109, v0
	v_mov_b32_e32 v110, v0
	v_mov_b32_e32 v111, v0
	v_mov_b32_e32 v116, v0
	v_mov_b32_e32 v117, v0
	v_mov_b32_e32 v118, v0
	v_mov_b32_e32 v119, v0
	v_mov_b32_e32 v120, v0
	v_mov_b32_e32 v121, v0
	v_mov_b32_e32 v122, v0
	v_mov_b32_e32 v123, v0
	v_mov_b32_e32 v124, v0
	v_mov_b32_e32 v125, v0
	v_mov_b32_e32 v126, v0
	v_mov_b32_e32 v127, v0
	s_setprio 1
.LBB0_683:
	s_cmpk_eq_i32 s2, 0x54
	s_cselect_b64 vcc, -1, 0
	s_add_i32 s3, 0, 0x10000
	v_add_u32_e32 v169, s3, v166
	s_add_i32 s8, 0, 0x14000
	ds_read_b128 v[176:179], v169
	ds_read_b128 v[180:183], v169 offset:1024
	ds_read_b128 v[184:187], v169 offset:2048
	ds_read_b128 v[188:191], v169 offset:3072
	v_add_u32_e32 v169, s8, v166
	ds_read_b128 v[192:195], v169
	ds_read_b128 v[196:199], v169 offset:1024
	ds_read_b128 v[200:203], v169 offset:2048
	ds_read_b128 v[204:207], v169 offset:3072
	v_lshl_add_u64 v[164:165], v[162:163], 0, s[82:83]
	v_cndmask_b32_e32 v241, v165, v157, vcc
	v_cndmask_b32_e32 v240, v164, v156, vcc
	v_cndmask_b32_e32 v243, v161, v159, vcc
	v_cndmask_b32_e32 v242, v160, v158, vcc
	v_lshl_add_u64 v[244:245], v[162:163], 0, v[154:155]
	s_add_i32 m0, s14, 0xc000
	ds_read_b128 v[208:211], v168
	ds_read_b128 v[212:215], v168 offset:1024
	ds_read_b128 v[216:219], v168 offset:2048
	ds_read_b128 v[220:223], v168 offset:3072
	ds_read_b128 v[224:227], v168 offset:4096
	ds_read_b128 v[228:231], v168 offset:5120
	ds_read_b128 v[232:235], v168 offset:6144
	ds_read_b128 v[236:239], v168 offset:7168
	global_load_lds_dwordx4 v[244:245], off
	v_lshl_add_u64 v[162:163], v[162:163], 0, v[152:153]
	s_add_i32 m0, s14, 0xe000
	s_nop 0
	global_load_lds_dwordx4 v[162:163], off
	s_setprio 0
	s_waitcnt vmcnt(8) lgkmcnt(0)
	s_barrier
	v_mfma_f32_16x16x32_bf16 v[124:127], v[176:179], v[208:211], v[124:127]
	v_mfma_f32_16x16x32_bf16 v[120:123], v[184:187], v[208:211], v[120:123]
	v_mfma_f32_16x16x32_bf16 v[116:119], v[176:179], v[216:219], v[116:119]
	v_mfma_f32_16x16x32_bf16 v[108:111], v[184:187], v[216:219], v[108:111]
	v_mfma_f32_16x16x32_bf16 v[100:103], v[176:179], v[224:227], v[100:103]
	v_mfma_f32_16x16x32_bf16 v[92:95], v[184:187], v[224:227], v[92:95]
	v_mfma_f32_16x16x32_bf16 v[84:87], v[176:179], v[232:235], v[84:87]
	v_mfma_f32_16x16x32_bf16 v[76:79], v[184:187], v[232:235], v[76:79]
	v_mfma_f32_16x16x32_bf16 v[124:127], v[180:183], v[212:215], v[124:127]
	v_mfma_f32_16x16x32_bf16 v[120:123], v[188:191], v[212:215], v[120:123]
	v_mfma_f32_16x16x32_bf16 v[116:119], v[180:183], v[220:223], v[116:119]
	v_mfma_f32_16x16x32_bf16 v[108:111], v[188:191], v[220:223], v[108:111]
	v_mfma_f32_16x16x32_bf16 v[100:103], v[180:183], v[228:231], v[100:103]
	v_mfma_f32_16x16x32_bf16 v[92:95], v[188:191], v[228:231], v[92:95]
	v_mfma_f32_16x16x32_bf16 v[84:87], v[180:183], v[236:239], v[84:87]
	v_mfma_f32_16x16x32_bf16 v[76:79], v[188:191], v[236:239], v[76:79]
	v_mfma_f32_16x16x32_bf16 v[112:115], v[192:195], v[208:211], v[112:115]
	v_mfma_f32_16x16x32_bf16 v[104:107], v[200:203], v[208:211], v[104:107]
	v_mfma_f32_16x16x32_bf16 v[96:99], v[192:195], v[216:219], v[96:99]
	v_mfma_f32_16x16x32_bf16 v[88:91], v[200:203], v[216:219], v[88:91]
	v_mfma_f32_16x16x32_bf16 v[80:83], v[192:195], v[224:227], v[80:83]
	v_mfma_f32_16x16x32_bf16 v[72:75], v[200:203], v[224:227], v[72:75]
	v_mfma_f32_16x16x32_bf16 v[68:71], v[192:195], v[232:235], v[68:71]
	v_mfma_f32_16x16x32_bf16 v[64:67], v[200:203], v[232:235], v[64:67]
	v_mfma_f32_16x16x32_bf16 v[112:115], v[196:199], v[212:215], v[112:115]
	v_mfma_f32_16x16x32_bf16 v[104:107], v[204:207], v[212:215], v[104:107]
	v_mfma_f32_16x16x32_bf16 v[96:99], v[196:199], v[220:223], v[96:99]
	v_mfma_f32_16x16x32_bf16 v[88:91], v[204:207], v[220:223], v[88:91]
	v_mfma_f32_16x16x32_bf16 v[80:83], v[196:199], v[228:231], v[80:83]
	v_mfma_f32_16x16x32_bf16 v[72:75], v[204:207], v[228:231], v[72:75]
	v_mfma_f32_16x16x32_bf16 v[68:71], v[196:199], v[236:239], v[68:71]
	v_mfma_f32_16x16x32_bf16 v[64:67], v[204:207], v[236:239], v[64:67]
	s_barrier
; #define PG8_STAGE(bufoff, gbase, voff) do { _Pragma("unroll") for (int _i = 0; _i < 2; ++_i) \
;         __builtin_amdgcn_global_load_lds((const unsigned*)((const char*)(gbase) + (voff)[_i]), (PG8_LAS unsigned*)(lds + (bufoff) + ldsw + _i * 8192), 16, 0, 0); } while (0)
; #define PG8_LDA(dst, b, h) do { _Pragma("unroll") for (int m = 0; m < 4; ++m) _Pragma("unroll") for (int k = 0; k < 2; ++k) dst[m][k] = *(const PG8_LAS bf16x8*)(lds + PG8_SA(b, h) + aoff + m * 2048 + k * 1024); } while (0)
; #define PG8_LDB(dst, b, h) do { _Pragma("unroll") for (int n = 0; n < 2; ++n) _Pragma("unroll") for (int k = 0; k < 2; ++k) dst[n][k] = *(const PG8_LAS bf16x8*)(lds + PG8_SB(b, h) + boff + n * 2048 + k * 1024); } while (0)
; #define PG8_MMA(ai, bj, At, Bt) do { __builtin_amdgcn_s_setprio(1); _Pragma("unroll") for (int m = 0; m < 4; ++m) _Pragma("unroll") for (int n = 0; n < 2; ++n) _Pragma("unroll") for (int k = 0; k < 2; ++k) \
;         acc[ai][bj][m][n] = __builtin_amdgcn_mfma_f32_16x16x32_bf16(Bt[n][k], At[m][k], acc[ai][bj][m][n], 0, 0, 0); __builtin_amdgcn_s_setprio(0); } while (0)
; #define PG8_WAIT_V(n) asm volatile("s_waitcnt vmcnt(" #n ")" ::: "memory")
; #define PG8_WAIT_L(n) asm volatile("s_waitcnt lgkmcnt(" #n ")" ::: "memory")
; #define PG8_BAR __builtin_amdgcn_s_barrier()
; #define PG8_SCHED __builtin_amdgcn_sched_barrier(0)
; template <class Epi, class Sched, bool ALIGN_EPI = false, bool SP2 = false>
; __device__ __forceinline__ void gemm_phase(PG8_LAS unsigned char* lds, const Gemm g, const Sched& S, const Epi& E, int tid_in) {
;     ...
;             PG8_LDA(At, 0, 1); PG8_STAGE(PG8_SB(0, 0), b2, voffB); PG8_STAGE(PG8_SB(0, 1), b2 + hstep, voffB); PG8_STAGE(PG8_SA(0, 0), a2, voffA);
;             PG8_WAIT_V(8); PG8_WAIT_L(0); PG8_BAR; PG8_MMA(1, 0, At, B0); PG8_MMA(1, 1, At, B1); PG8_BAR; PG8_SCHED;
;             PG8_LDB(B0, 1, 0); PG8_LDB(B1, 1, 1); PG8_SCHED; PG8_LDA(At, 1, 0); PG8_STAGE(PG8_SA(0, 1), a2 + hstep, voffA);
;             PG8_WAIT_V(8); PG8_WAIT_L(0); PG8_BAR; PG8_MMA(0, 0, At, B0); PG8_MMA(0, 1, At, B1); PG8_BAR; PG8_SCHED;
	s_setprio 1
	s_add_i32 s3, s3, s1
	v_lshl_add_u64 v[162:163], v[242:243], 0, v[128:129]
	s_mov_b32 m0, s3
	ds_read_b128 v[208:211], v168 offset:16384
	ds_read_b128 v[212:215], v168 offset:17408
	ds_read_b128 v[216:219], v168 offset:18432
	ds_read_b128 v[220:223], v168 offset:19456
	ds_read_b128 v[224:227], v168 offset:20480
	ds_read_b128 v[228:231], v168 offset:21504
	ds_read_b128 v[232:235], v168 offset:22528
	ds_read_b128 v[236:239], v168 offset:23552
	global_load_lds_dwordx4 v[162:163], off
	v_lshl_add_u64 v[244:245], v[242:243], 0, v[144:145]
	s_add_i32 m0, s3, 0x2000
	v_lshl_add_u64 v[246:247], v[242:243], 0, s[74:75]
	s_add_i32 s3, s8, s1
	global_load_lds_dwordx4 v[244:245], off
	v_lshl_add_u64 v[248:249], v[246:247], 0, v[128:129]
	s_mov_b32 m0, s3
	v_lshl_add_u64 v[246:247], v[246:247], 0, v[144:145]
	global_load_lds_dwordx4 v[248:249], off
	s_add_i32 m0, s3, 0x2000
	v_lshl_add_u64 v[248:249], v[240:241], 0, v[146:147]
	global_load_lds_dwordx4 v[246:247], off
	v_lshl_add_u64 v[246:247], v[240:241], 0, v[148:149]
	s_mov_b32 m0, s14
	s_nop 0
	global_load_lds_dwordx4 v[246:247], off
	s_mov_b32 m0, s15
	s_nop 0
	global_load_lds_dwordx4 v[248:249], off
	s_setprio 0
	s_waitcnt vmcnt(8) lgkmcnt(0)
	s_barrier
	v_mfma_f32_16x16x32_bf16 v[60:63], v[176:179], v[208:211], v[60:63]
	v_mfma_f32_16x16x32_bf16 v[56:59], v[184:187], v[208:211], v[56:59]
	v_mfma_f32_16x16x32_bf16 v[52:55], v[176:179], v[216:219], v[52:55]
	v_mfma_f32_16x16x32_bf16 v[44:47], v[184:187], v[216:219], v[44:47]
	v_mfma_f32_16x16x32_bf16 v[36:39], v[176:179], v[224:227], v[36:39]
	v_mfma_f32_16x16x32_bf16 v[28:31], v[184:187], v[224:227], v[28:31]
	v_mfma_f32_16x16x32_bf16 v[20:23], v[176:179], v[232:235], v[20:23]
	v_mfma_f32_16x16x32_bf16 v[12:15], v[184:187], v[232:235], v[12:15]
	v_mfma_f32_16x16x32_bf16 v[60:63], v[180:183], v[212:215], v[60:63]
	v_mfma_f32_16x16x32_bf16 v[56:59], v[188:191], v[212:215], v[56:59]
	v_mfma_f32_16x16x32_bf16 v[52:55], v[180:183], v[220:223], v[52:55]
	v_mfma_f32_16x16x32_bf16 v[44:47], v[188:191], v[220:223], v[44:47]
	v_mfma_f32_16x16x32_bf16 v[36:39], v[180:183], v[228:231], v[36:39]
	v_mfma_f32_16x16x32_bf16 v[28:31], v[188:191], v[228:231], v[28:31]
	v_mfma_f32_16x16x32_bf16 v[20:23], v[180:183], v[236:239], v[20:23]
	v_mfma_f32_16x16x32_bf16 v[12:15], v[188:191], v[236:239], v[12:15]
	v_mfma_f32_16x16x32_bf16 v[48:51], v[192:195], v[208:211], v[48:51]
	v_mfma_f32_16x16x32_bf16 v[40:43], v[200:203], v[208:211], v[40:43]
	v_mfma_f32_16x16x32_bf16 v[32:35], v[192:195], v[216:219], v[32:35]
	v_mfma_f32_16x16x32_bf16 v[24:27], v[200:203], v[216:219], v[24:27]
	v_mfma_f32_16x16x32_bf16 v[16:19], v[192:195], v[224:227], v[16:19]
	v_mfma_f32_16x16x32_bf16 v[8:11], v[200:203], v[224:227], v[8:11]
	v_mfma_f32_16x16x32_bf16 v[4:7], v[192:195], v[232:235], v[4:7]
	v_mfma_f32_16x16x32_bf16 v[0:3], v[200:203], v[232:235], v[0:3]
	v_mfma_f32_16x16x32_bf16 v[48:51], v[196:199], v[212:215], v[48:51]
	v_mfma_f32_16x16x32_bf16 v[40:43], v[204:207], v[212:215], v[40:43]
	v_mfma_f32_16x16x32_bf16 v[32:35], v[196:199], v[220:223], v[32:35]
	v_mfma_f32_16x16x32_bf16 v[24:27], v[204:207], v[220:223], v[24:27]
	v_mfma_f32_16x16x32_bf16 v[16:19], v[196:199], v[228:231], v[16:19]
	v_mfma_f32_16x16x32_bf16 v[8:11], v[204:207], v[228:231], v[8:11]
	v_mfma_f32_16x16x32_bf16 v[4:7], v[196:199], v[236:239], v[4:7]
	v_mfma_f32_16x16x32_bf16 v[0:3], v[204:207], v[236:239], v[0:3]
	s_barrier
	s_setprio 1
	s_add_i32 s3, 0, 0x18000
	v_add_u32_e32 v169, s3, v166
	s_add_i32 s8, 0, 0x1c000
	ds_read_b128 v[176:179], v169
	ds_read_b128 v[180:183], v169 offset:1024
	ds_read_b128 v[184:187], v169 offset:2048
	ds_read_b128 v[188:191], v169 offset:3072
	v_add_u32_e32 v169, s8, v166
	ds_read_b128 v[192:195], v169
	ds_read_b128 v[196:199], v169 offset:1024
	ds_read_b128 v[200:203], v169 offset:2048
	ds_read_b128 v[204:207], v169 offset:3072
	v_lshl_add_u64 v[240:241], v[240:241], 0, s[74:75]
	s_mov_b32 m0, s16
	v_lshl_add_u64 v[250:251], v[240:241], 0, v[148:149]
	ds_read_b128 v[208:211], v168 offset:32768
	ds_read_b128 v[212:215], v168 offset:33792
	ds_read_b128 v[216:219], v168 offset:34816
	ds_read_b128 v[220:223], v168 offset:35840
	ds_read_b128 v[224:227], v168 offset:36864
	ds_read_b128 v[228:231], v168 offset:37888
	ds_read_b128 v[232:235], v168 offset:38912
	ds_read_b128 v[236:239], v168 offset:39936
	global_load_lds_dwordx4 v[250:251], off
	v_lshl_add_u64 v[240:241], v[240:241], 0, v[146:147]
	s_mov_b32 m0, s17
	s_nop 0
	global_load_lds_dwordx4 v[240:241], off
	s_setprio 0
	s_waitcnt vmcnt(8) lgkmcnt(0)
	s_barrier
; #define PG8_STAGE(bufoff, gbase, voff) do { _Pragma("unroll") for (int _i = 0; _i < 2; ++_i) \
;         __builtin_amdgcn_global_load_lds((const unsigned*)((const char*)(gbase) + (voff)[_i]), (PG8_LAS unsigned*)(lds + (bufoff) + ldsw + _i * 8192), 16, 0, 0); } while (0)
; #define PG8_LDA(dst, b, h) do { _Pragma("unroll") for (int m = 0; m < 4; ++m) _Pragma("unroll") for (int k = 0; k < 2; ++k) dst[m][k] = *(const PG8_LAS bf16x8*)(lds + PG8_SA(b, h) + aoff + m * 2048 + k * 1024); } while (0)
; #define PG8_MMA(ai, bj, At, Bt) do { __builtin_amdgcn_s_setprio(1); _Pragma("unroll") for (int m = 0; m < 4; ++m) _Pragma("unroll") for (int n = 0; n < 2; ++n) _Pragma("unroll") for (int k = 0; k < 2; ++k) \
;         acc[ai][bj][m][n] = __builtin_amdgcn_mfma_f32_16x16x32_bf16(Bt[n][k], At[m][k], acc[ai][bj][m][n], 0, 0, 0); __builtin_amdgcn_s_setprio(0); } while (0)
; #define PG8_WAIT_V(n) asm volatile("s_waitcnt vmcnt(" #n ")" ::: "memory")
; #define PG8_WAIT_L(n) asm volatile("s_waitcnt lgkmcnt(" #n ")" ::: "memory")
; #define PG8_BAR __builtin_amdgcn_s_barrier()
; #define PG8_SCHED __builtin_amdgcn_sched_barrier(0)
; template <class Epi, class Sched, bool ALIGN_EPI = false, bool SP2 = false>
; __device__ __forceinline__ void gemm_phase(PG8_LAS unsigned char* lds, const Gemm g, const Sched& S, const Epi& E, int tid_in) {
;     ...
;         for (int t = 0; t < nt; t += 2) {
;             const bool last = (t == nt - 2);
;     ...
;             PG8_WAIT_V(8); PG8_WAIT_L(0); PG8_BAR; PG8_MMA(0, 0, At, B0); PG8_MMA(0, 1, At, B1); PG8_BAR; PG8_SCHED;
;             PG8_LDA(At, 1, 1); PG8_STAGE(PG8_SB(1, 0), b3, voffB); PG8_STAGE(PG8_SB(1, 1), b3 + hstep, voffB); PG8_STAGE(PG8_SA(1, 0), a3, voffA);
;             PG8_WAIT_V(8); PG8_WAIT_L(0); PG8_BAR; PG8_MMA(1, 0, At, B0); PG8_MMA(1, 1, At, B1); PG8_BAR; PG8_SCHED;
	v_mfma_f32_16x16x32_bf16 v[124:127], v[176:179], v[208:211], v[124:127]
	v_mfma_f32_16x16x32_bf16 v[120:123], v[184:187], v[208:211], v[120:123]
	v_mfma_f32_16x16x32_bf16 v[116:119], v[176:179], v[216:219], v[116:119]
	v_mfma_f32_16x16x32_bf16 v[108:111], v[184:187], v[216:219], v[108:111]
	v_mfma_f32_16x16x32_bf16 v[100:103], v[176:179], v[224:227], v[100:103]
	v_mfma_f32_16x16x32_bf16 v[92:95], v[184:187], v[224:227], v[92:95]
	v_mfma_f32_16x16x32_bf16 v[84:87], v[176:179], v[232:235], v[84:87]
	v_mfma_f32_16x16x32_bf16 v[76:79], v[184:187], v[232:235], v[76:79]
	v_mfma_f32_16x16x32_bf16 v[124:127], v[180:183], v[212:215], v[124:127]
	v_mfma_f32_16x16x32_bf16 v[120:123], v[188:191], v[212:215], v[120:123]
	v_mfma_f32_16x16x32_bf16 v[116:119], v[180:183], v[220:223], v[116:119]
	v_mfma_f32_16x16x32_bf16 v[108:111], v[188:191], v[220:223], v[108:111]
	v_mfma_f32_16x16x32_bf16 v[100:103], v[180:183], v[228:231], v[100:103]
	v_mfma_f32_16x16x32_bf16 v[92:95], v[188:191], v[228:231], v[92:95]
	v_mfma_f32_16x16x32_bf16 v[84:87], v[180:183], v[236:239], v[84:87]
	v_mfma_f32_16x16x32_bf16 v[76:79], v[188:191], v[236:239], v[76:79]
	v_mfma_f32_16x16x32_bf16 v[112:115], v[192:195], v[208:211], v[112:115]
	v_mfma_f32_16x16x32_bf16 v[104:107], v[200:203], v[208:211], v[104:107]
	v_mfma_f32_16x16x32_bf16 v[96:99], v[192:195], v[216:219], v[96:99]
	v_mfma_f32_16x16x32_bf16 v[88:91], v[200:203], v[216:219], v[88:91]
	v_mfma_f32_16x16x32_bf16 v[80:83], v[192:195], v[224:227], v[80:83]
	v_mfma_f32_16x16x32_bf16 v[72:75], v[200:203], v[224:227], v[72:75]
	v_mfma_f32_16x16x32_bf16 v[68:71], v[192:195], v[232:235], v[68:71]
	v_mfma_f32_16x16x32_bf16 v[64:67], v[200:203], v[232:235], v[64:67]
	v_mfma_f32_16x16x32_bf16 v[112:115], v[196:199], v[212:215], v[112:115]
	v_mfma_f32_16x16x32_bf16 v[104:107], v[204:207], v[212:215], v[104:107]
	v_mfma_f32_16x16x32_bf16 v[96:99], v[196:199], v[220:223], v[96:99]
	v_mfma_f32_16x16x32_bf16 v[88:91], v[204:207], v[220:223], v[88:91]
	v_mfma_f32_16x16x32_bf16 v[80:83], v[196:199], v[228:231], v[80:83]
	v_mfma_f32_16x16x32_bf16 v[72:75], v[204:207], v[228:231], v[72:75]
	v_mfma_f32_16x16x32_bf16 v[68:71], v[196:199], v[236:239], v[68:71]
	v_mfma_f32_16x16x32_bf16 v[64:67], v[204:207], v[236:239], v[64:67]
	s_barrier
	s_setprio 1
	s_add_i32 s3, s3, s1
	v_lshl_add_u64 v[162:163], v[162:163], 0, s[70:71]
	s_mov_b32 m0, s3
	ds_read_b128 v[208:211], v168 offset:49152
	ds_read_b128 v[212:215], v168 offset:50176
	ds_read_b128 v[216:219], v168 offset:51200
	ds_read_b128 v[220:223], v168 offset:52224
	ds_read_b128 v[224:227], v168 offset:53248
	ds_read_b128 v[228:231], v168 offset:54272
	ds_read_b128 v[232:235], v168 offset:55296
	ds_read_b128 v[236:239], v168 offset:56320
	global_load_lds_dwordx4 v[162:163], off
	v_lshl_add_u64 v[162:163], v[244:245], 0, s[70:71]
	s_add_i32 m0, s3, 0x2000
	s_add_i32 s3, s8, s1
	global_load_lds_dwordx4 v[162:163], off
	v_lshl_add_u64 v[162:163], v[242:243], 0, s[60:61]
	v_lshl_add_u64 v[240:241], v[162:163], 0, v[128:129]
	s_mov_b32 m0, s3
	v_lshl_add_u64 v[162:163], v[162:163], 0, v[144:145]
	global_load_lds_dwordx4 v[240:241], off
	s_add_i32 m0, s3, 0x2000
	s_nop 0
	global_load_lds_dwordx4 v[162:163], off
	v_lshl_add_u64 v[162:163], v[246:247], 0, s[70:71]
	s_mov_b32 m0, s18
	s_nop 0
	global_load_lds_dwordx4 v[162:163], off
	v_lshl_add_u64 v[162:163], v[248:249], 0, s[70:71]
	s_mov_b32 m0, s19
	s_nop 0
	global_load_lds_dwordx4 v[162:163], off
	s_setprio 0
	s_waitcnt vmcnt(8) lgkmcnt(0)
	s_barrier
	v_mfma_f32_16x16x32_bf16 v[60:63], v[176:179], v[208:211], v[60:63]
	v_mfma_f32_16x16x32_bf16 v[56:59], v[184:187], v[208:211], v[56:59]
	v_mfma_f32_16x16x32_bf16 v[52:55], v[176:179], v[216:219], v[52:55]
	v_mfma_f32_16x16x32_bf16 v[44:47], v[184:187], v[216:219], v[44:47]
	v_mfma_f32_16x16x32_bf16 v[36:39], v[176:179], v[224:227], v[36:39]
	v_mfma_f32_16x16x32_bf16 v[28:31], v[184:187], v[224:227], v[28:31]
	v_mfma_f32_16x16x32_bf16 v[20:23], v[176:179], v[232:235], v[20:23]
	v_mfma_f32_16x16x32_bf16 v[12:15], v[184:187], v[232:235], v[12:15]
	v_mfma_f32_16x16x32_bf16 v[60:63], v[180:183], v[212:215], v[60:63]
	v_mfma_f32_16x16x32_bf16 v[56:59], v[188:191], v[212:215], v[56:59]
	v_mfma_f32_16x16x32_bf16 v[52:55], v[180:183], v[220:223], v[52:55]
	v_mfma_f32_16x16x32_bf16 v[44:47], v[188:191], v[220:223], v[44:47]
	v_mfma_f32_16x16x32_bf16 v[36:39], v[180:183], v[228:231], v[36:39]
	v_mfma_f32_16x16x32_bf16 v[28:31], v[188:191], v[228:231], v[28:31]
	v_mfma_f32_16x16x32_bf16 v[20:23], v[180:183], v[236:239], v[20:23]
	v_mfma_f32_16x16x32_bf16 v[12:15], v[188:191], v[236:239], v[12:15]
	v_mfma_f32_16x16x32_bf16 v[48:51], v[192:195], v[208:211], v[48:51]
	v_mfma_f32_16x16x32_bf16 v[40:43], v[200:203], v[208:211], v[40:43]
	v_mfma_f32_16x16x32_bf16 v[32:35], v[192:195], v[216:219], v[32:35]
	v_mfma_f32_16x16x32_bf16 v[24:27], v[200:203], v[216:219], v[24:27]
	v_mfma_f32_16x16x32_bf16 v[16:19], v[192:195], v[224:227], v[16:19]
	v_mfma_f32_16x16x32_bf16 v[8:11], v[200:203], v[224:227], v[8:11]
	v_mfma_f32_16x16x32_bf16 v[4:7], v[192:195], v[232:235], v[4:7]
	v_mfma_f32_16x16x32_bf16 v[0:3], v[200:203], v[232:235], v[0:3]
	v_mfma_f32_16x16x32_bf16 v[48:51], v[196:199], v[212:215], v[48:51]
	v_mfma_f32_16x16x32_bf16 v[40:43], v[204:207], v[212:215], v[40:43]
	v_mfma_f32_16x16x32_bf16 v[32:35], v[196:199], v[220:223], v[32:35]
	v_mfma_f32_16x16x32_bf16 v[24:27], v[204:207], v[220:223], v[24:27]
	v_mfma_f32_16x16x32_bf16 v[16:19], v[196:199], v[228:231], v[16:19]
	v_mfma_f32_16x16x32_bf16 v[8:11], v[204:207], v[228:231], v[8:11]
	v_mfma_f32_16x16x32_bf16 v[4:7], v[196:199], v[236:239], v[4:7]
	v_mfma_f32_16x16x32_bf16 v[0:3], v[204:207], v[236:239], v[0:3]
	s_barrier
	s_setprio 1
	s_add_i32 s2, s2, 2
	v_lshl_add_u64 v[160:161], v[160:161], 0, s[82:83]
	s_cmpk_gt_u32 s2, 0x55
	v_mov_b64_e32 v[162:163], v[164:165]
	s_cbranch_scc0 .LBB0_683
	s_setprio 0
	s_and_b64 vcc, exec, s[12:13]
	s_cbranch_vccz .LBB0_686
	s_barrier
